# int8 GEMM epilogues: the 8 row-scale dword loads become 2 coalesced loads + 8 ds_bpermute (6 fewer vector-memory instructions per wave and epilogue)
# speedup vs baseline: 1.0001x; 1.0001x over previous
; __device__ __forceinline__ unsigned cvt_pk_bf16(float lo, float hi) { unsigned r; asm("v_cvt_pk_bf16_f32 %0, %1, %2" : "=v"(r) : "v"(lo), "v"(hi)); return r; }
;     __device__ __forceinline__ void operator()(const f32x4 (&acc)[2][2][4][2], const pg8::Unit& u, int wr, int wc, int fr, int fq) const {
;     ...
;         float sav[2][4];
; #pragma unroll
;         for (int ai = 0; ai < 2; ++ai)
; #pragma unroll
;             for (int m = 0; m < 4; ++m) sav[ai][m] = sa[row0 + ai * 128 + m * 16];
; #pragma unroll
;         for (int am = 0; am < 4; ++am) { const int ai = am >> 1, m0 = 2 * (am & 1); f32x4 r[2][2][2];
; #pragma unroll
;             for (int mm = 0; mm < 2; ++mm) { const int row = row0 + ai * 128 + (m0 + mm) * 16; const float* xin = (row < MP ? xp + (size_t)row * DM : xs + (size_t)(row - MP) * DM) + col0;
; #pragma unroll
;                 for (int bj = 0; bj < 2; ++bj)
; #pragma unroll
;                     for (int n = 0; n < 2; ++n) r[mm][bj][n] = *(const f32x4*)(xin + bj * 128 + n * 16); }
; #pragma unroll
;             for (int mm = 0; mm < 2; ++mm) { const size_t off = (size_t)(row0 + ai * 128 + (m0 + mm) * 16) * DM + col0;
; #pragma unroll
;                 for (int bj = 0; bj < 2; ++bj)
; #pragma unroll
;                     for (int n = 0; n < 2; ++n) { const i32x4 q = __builtin_bit_cast(i32x4, acc[ai][bj][m0 + mm][n]);
;                         const f32x4 v = (f32x4){(float)q[0], (float)q[1], (float)q[2], (float)q[3]} * swv[bj][n] * sav[ai][m0 + mm] + r[mm][bj][n];
;                         u32x2 w; w.x = cvt_pk_bf16(v[0], v[1]); w.y = cvt_pk_bf16(v[2], v[3]); *(u32x2*)(X1 + off + bj * 128 + n * 16) = w; } } }
.LBB0_2234:
	v_readlane_b32 s58, v254, 2
	v_readlane_b32 s59, v254, 3
	v_readlane_b32 s100, v254, 4
	v_readlane_b32 s101, v254, 5
	v_lshl_add_u32 v156, s28, 8, v163
	v_and_b32_e32 v157, 1, v235
	v_mul_u32_u24_e32 v157, 12, v157
	v_add_u32_e32 v157, v157, v165
	v_lshl_or_b32 v157, s56, 8, v157
	s_sub_u32 s100, s100, 0x8000000
	s_subb_u32 s101, s101, 0
	s_cmp_lt_i32 s28, 32
	s_cselect_b32 s58, s58, s100
	s_cselect_b32 s59, s59, s101
	v_lshlrev_b32_e32 v159, 2, v157
	v_lshlrev_b32_e32 v160, 13, v156
	v_lshl_add_u32 v160, v157, 1, v160
	v_lshlrev_b32_e32 v161, 14, v156
	v_lshl_add_u32 v161, v157, 2, v161
	v_mbcnt_lo_u32_b32 v158, -1, 0
	v_mbcnt_hi_u32_b32 v158, -1, v158
	v_and_b32_e32 v208, 64, v163
	v_add_u32_e32 v158, v158, v208
	v_lshl_add_u32 v158, s28, 8, v158
	v_lshlrev_b32_e32 v158, 2, v158
	v_and_b32_e32 v208, 15, v163
	v_lshlrev_b32_e32 v208, 2, v208
	global_load_dword v206, v158, s[6:7]
	global_load_dword v207, v158, s[6:7] offset:512
	global_load_dwordx4 v[114:117], v159, s[8:9] offset:0
	global_load_dwordx4 v[118:121], v159, s[8:9] offset:16
	global_load_dwordx4 v[170:173], v159, s[8:9] offset:512
	global_load_dwordx4 v[174:177], v159, s[8:9] offset:528
	v_mov_b32_e32 v162, v161
	global_load_dwordx4 v[178:181], v162, s[58:59] offset:0
	global_load_dwordx4 v[182:185], v162, s[58:59] offset:16
	v_mov_b32_e32 v231, v161
	global_load_dwordx4 v[186:189], v231, s[58:59] offset:512
	global_load_dwordx4 v[190:193], v231, s[58:59] offset:528
	v_add_u32_e32 v162, 0x40000, v161
	global_load_dwordx4 v[194:197], v162, s[58:59] offset:0
	global_load_dwordx4 v[198:201], v162, s[58:59] offset:16
	v_add_u32_e32 v231, 0x40000, v161
	global_load_dwordx4 v[202:205], v231, s[58:59] offset:512
	global_load_dwordx4 v[214:217], v231, s[58:59] offset:528
	v_add_u32_e32 v162, 0x80000, v161
	global_load_dwordx4 v[218:221], v162, s[58:59] offset:0
	global_load_dwordx4 v[222:225], v162, s[58:59] offset:16
	v_permlane16_swap_b32_e32 v142, v138
	v_permlane16_swap_b32_e32 v143, v139
	v_permlane16_swap_b32_e32 v144, v140
	v_permlane16_swap_b32_e32 v145, v141
	v_cvt_f32_i32_e32 v142, v142
	v_cvt_f32_i32_e32 v143, v143
	v_cvt_f32_i32_e32 v144, v144
	v_cvt_f32_i32_e32 v145, v145
	v_cvt_f32_i32_e32 v138, v138
	v_cvt_f32_i32_e32 v139, v139
	v_cvt_f32_i32_e32 v140, v140
	v_cvt_f32_i32_e32 v141, v141
	s_waitcnt vmcnt(8)
	ds_bpermute_b32 v102, v208, v206
	ds_bpermute_b32 v103, v208, v206 offset:64
	ds_bpermute_b32 v104, v208, v206 offset:128
	ds_bpermute_b32 v105, v208, v206 offset:192
	ds_bpermute_b32 v106, v208, v207
	ds_bpermute_b32 v107, v208, v207 offset:64
	ds_bpermute_b32 v108, v208, v207 offset:128
	ds_bpermute_b32 v109, v208, v207 offset:192
	s_waitcnt lgkmcnt(0)
	v_pk_mul_f32 v[142:143], v[142:143], v[114:115]
	v_pk_mul_f32 v[144:145], v[144:145], v[116:117]
	v_pk_mul_f32 v[138:139], v[138:139], v[118:119]
	v_pk_mul_f32 v[140:141], v[140:141], v[120:121]
	v_fma_f32 v142, v142, v102, v178
	v_fma_f32 v143, v143, v102, v179
	v_fma_f32 v144, v144, v102, v180
	v_fma_f32 v145, v145, v102, v181
	v_fma_f32 v138, v138, v102, v182
	v_fma_f32 v139, v139, v102, v183
	v_fma_f32 v140, v140, v102, v184
	v_fma_f32 v141, v141, v102, v185
	v_cvt_pk_bf16_f32 v142, v142, v143
	v_cvt_pk_bf16_f32 v143, v144, v145
	v_cvt_pk_bf16_f32 v144, v138, v139
	v_cvt_pk_bf16_f32 v145, v140, v141
	v_permlane16_swap_b32_e32 v134, v130
	v_permlane16_swap_b32_e32 v135, v131
	v_permlane16_swap_b32_e32 v136, v132
	v_permlane16_swap_b32_e32 v137, v133
	v_cvt_f32_i32_e32 v134, v134
	v_cvt_f32_i32_e32 v135, v135
	v_cvt_f32_i32_e32 v136, v136
	v_cvt_f32_i32_e32 v137, v137
	v_cvt_f32_i32_e32 v130, v130
	v_cvt_f32_i32_e32 v131, v131
	v_cvt_f32_i32_e32 v132, v132
	v_cvt_f32_i32_e32 v133, v133
	s_waitcnt vmcnt(6)
	v_pk_mul_f32 v[134:135], v[134:135], v[170:171]
	v_pk_mul_f32 v[136:137], v[136:137], v[172:173]
	v_pk_mul_f32 v[130:131], v[130:131], v[174:175]
	v_pk_mul_f32 v[132:133], v[132:133], v[176:177]
	v_fma_f32 v134, v134, v102, v186
	v_fma_f32 v135, v135, v102, v187
	v_fma_f32 v136, v136, v102, v188
	v_fma_f32 v137, v137, v102, v189
	v_fma_f32 v130, v130, v102, v190
	v_fma_f32 v131, v131, v102, v191
	v_fma_f32 v132, v132, v102, v192
	v_fma_f32 v133, v133, v102, v193
	v_cvt_pk_bf16_f32 v134, v134, v135
	v_cvt_pk_bf16_f32 v135, v136, v137
	v_cvt_pk_bf16_f32 v136, v130, v131
	v_cvt_pk_bf16_f32 v137, v132, v133
	v_add_u32_e32 v231, 0x80000, v161
	global_load_dwordx4 v[138:141], v231, s[58:59] offset:512
	global_load_dwordx4 v[130:133], v231, s[58:59] offset:528
	v_permlane16_swap_b32_e32 v126, v122
	v_permlane16_swap_b32_e32 v127, v123
	v_permlane16_swap_b32_e32 v128, v124
	v_permlane16_swap_b32_e32 v129, v125
	v_cvt_f32_i32_e32 v126, v126
	v_cvt_f32_i32_e32 v127, v127
	v_cvt_f32_i32_e32 v128, v128
	v_cvt_f32_i32_e32 v129, v129
	v_cvt_f32_i32_e32 v122, v122
	v_cvt_f32_i32_e32 v123, v123
	v_cvt_f32_i32_e32 v124, v124
	v_cvt_f32_i32_e32 v125, v125
	s_waitcnt vmcnt(6)
	v_pk_mul_f32 v[126:127], v[126:127], v[114:115]
	v_pk_mul_f32 v[128:129], v[128:129], v[116:117]
	v_pk_mul_f32 v[122:123], v[122:123], v[118:119]
	v_pk_mul_f32 v[124:125], v[124:125], v[120:121]
	v_fma_f32 v126, v126, v103, v194
	v_fma_f32 v127, v127, v103, v195
	v_fma_f32 v128, v128, v103, v196
	v_fma_f32 v129, v129, v103, v197
	v_fma_f32 v122, v122, v103, v198
	v_fma_f32 v123, v123, v103, v199
	v_fma_f32 v124, v124, v103, v200
	v_fma_f32 v125, v125, v103, v201
	v_cvt_pk_bf16_f32 v126, v126, v127
	v_cvt_pk_bf16_f32 v127, v128, v129
	v_cvt_pk_bf16_f32 v128, v122, v123
	v_cvt_pk_bf16_f32 v129, v124, v125
	v_permlane16_swap_b32_e32 v110, v98
	v_permlane16_swap_b32_e32 v111, v99
	v_permlane16_swap_b32_e32 v112, v100
	v_permlane16_swap_b32_e32 v113, v101
	v_cvt_f32_i32_e32 v110, v110
	v_cvt_f32_i32_e32 v111, v111
	v_cvt_f32_i32_e32 v112, v112
	v_cvt_f32_i32_e32 v113, v113
	v_cvt_f32_i32_e32 v98, v98
	v_cvt_f32_i32_e32 v99, v99
	v_cvt_f32_i32_e32 v100, v100
	v_cvt_f32_i32_e32 v101, v101
	s_waitcnt vmcnt(4)
; __device__ __forceinline__ unsigned cvt_pk_bf16(float lo, float hi) { unsigned r; asm("v_cvt_pk_bf16_f32 %0, %1, %2" : "=v"(r) : "v"(lo), "v"(hi)); return r; }
;     __device__ __forceinline__ void operator()(const f32x4 (&acc)[2][2][4][2], const pg8::Unit& u, int wr, int wc, int fr, int fq) const {
;     ...
;         for (int am = 0; am < 4; ++am) { const int ai = am >> 1, m0 = 2 * (am & 1); f32x4 r[2][2][2];
; #pragma unroll
;             for (int mm = 0; mm < 2; ++mm) { const int row = row0 + ai * 128 + (m0 + mm) * 16; const float* xin = (row < MP ? xp + (size_t)row * DM : xs + (size_t)(row - MP) * DM) + col0;
; #pragma unroll
;                 for (int bj = 0; bj < 2; ++bj)
; #pragma unroll
;                     for (int n = 0; n < 2; ++n) r[mm][bj][n] = *(const f32x4*)(xin + bj * 128 + n * 16); }
; #pragma unroll
;             for (int mm = 0; mm < 2; ++mm) { const size_t off = (size_t)(row0 + ai * 128 + (m0 + mm) * 16) * DM + col0;
; #pragma unroll
;                 for (int bj = 0; bj < 2; ++bj)
; #pragma unroll
;                     for (int n = 0; n < 2; ++n) { const i32x4 q = __builtin_bit_cast(i32x4, acc[ai][bj][m0 + mm][n]);
;                         const f32x4 v = (f32x4){(float)q[0], (float)q[1], (float)q[2], (float)q[3]} * swv[bj][n] * sav[ai][m0 + mm] + r[mm][bj][n];
;                         u32x2 w; w.x = cvt_pk_bf16(v[0], v[1]); w.y = cvt_pk_bf16(v[2], v[3]); *(u32x2*)(X1 + off + bj * 128 + n * 16) = w; } } }
	v_pk_mul_f32 v[110:111], v[110:111], v[170:171]
	v_pk_mul_f32 v[112:113], v[112:113], v[172:173]
	v_pk_mul_f32 v[98:99], v[98:99], v[174:175]
	v_pk_mul_f32 v[100:101], v[100:101], v[176:177]
	v_fma_f32 v110, v110, v103, v202
	v_fma_f32 v111, v111, v103, v203
	v_fma_f32 v112, v112, v103, v204
	v_fma_f32 v113, v113, v103, v205
	v_fma_f32 v98, v98, v103, v214
	v_fma_f32 v99, v99, v103, v215
	v_fma_f32 v100, v100, v103, v216
	v_fma_f32 v101, v101, v103, v217
	v_cvt_pk_bf16_f32 v110, v110, v111
	v_cvt_pk_bf16_f32 v111, v112, v113
	v_cvt_pk_bf16_f32 v112, v98, v99
	v_cvt_pk_bf16_f32 v113, v100, v101
	v_add_u32_e32 v162, 0xc0000, v161
	global_load_dwordx4 v[122:125], v162, s[58:59] offset:0
	global_load_dwordx4 v[98:101], v162, s[58:59] offset:16
	v_permlane16_swap_b32_e32 v94, v90
	v_permlane16_swap_b32_e32 v95, v91
	v_permlane16_swap_b32_e32 v96, v92
	v_permlane16_swap_b32_e32 v97, v93
	v_cvt_f32_i32_e32 v94, v94
	v_cvt_f32_i32_e32 v95, v95
	v_cvt_f32_i32_e32 v96, v96
	v_cvt_f32_i32_e32 v97, v97
	v_cvt_f32_i32_e32 v90, v90
	v_cvt_f32_i32_e32 v91, v91
	v_cvt_f32_i32_e32 v92, v92
	v_cvt_f32_i32_e32 v93, v93
	s_waitcnt vmcnt(4)
	v_pk_mul_f32 v[94:95], v[94:95], v[114:115]
	v_pk_mul_f32 v[96:97], v[96:97], v[116:117]
	v_pk_mul_f32 v[90:91], v[90:91], v[118:119]
	v_pk_mul_f32 v[92:93], v[92:93], v[120:121]
	v_fma_f32 v94, v94, v104, v218
	v_fma_f32 v95, v95, v104, v219
	v_fma_f32 v96, v96, v104, v220
	v_fma_f32 v97, v97, v104, v221
	v_fma_f32 v90, v90, v104, v222
	v_fma_f32 v91, v91, v104, v223
	v_fma_f32 v92, v92, v104, v224
	v_fma_f32 v93, v93, v104, v225
	v_cvt_pk_bf16_f32 v94, v94, v95
	v_cvt_pk_bf16_f32 v95, v96, v97
	v_cvt_pk_bf16_f32 v96, v90, v91
	v_cvt_pk_bf16_f32 v97, v92, v93
	v_add_u32_e32 v231, 0xc0000, v161
	global_load_dwordx4 v[178:181], v231, s[58:59] offset:512
	global_load_dwordx4 v[182:185], v231, s[58:59] offset:528
	v_permlane16_swap_b32_e32 v86, v78
	v_permlane16_swap_b32_e32 v87, v79
	v_permlane16_swap_b32_e32 v88, v80
	v_permlane16_swap_b32_e32 v89, v81
	v_cvt_f32_i32_e32 v86, v86
	v_cvt_f32_i32_e32 v87, v87
	v_cvt_f32_i32_e32 v88, v88
	v_cvt_f32_i32_e32 v89, v89
	v_cvt_f32_i32_e32 v78, v78
	v_cvt_f32_i32_e32 v79, v79
	v_cvt_f32_i32_e32 v80, v80
	v_cvt_f32_i32_e32 v81, v81
	s_waitcnt vmcnt(4)
	v_pk_mul_f32 v[86:87], v[86:87], v[170:171]
	v_pk_mul_f32 v[88:89], v[88:89], v[172:173]
	v_pk_mul_f32 v[78:79], v[78:79], v[174:175]
	v_pk_mul_f32 v[80:81], v[80:81], v[176:177]
	v_fma_f32 v86, v86, v104, v138
	v_fma_f32 v87, v87, v104, v139
	v_fma_f32 v88, v88, v104, v140
	v_fma_f32 v89, v89, v104, v141
	v_fma_f32 v78, v78, v104, v130
	v_fma_f32 v79, v79, v104, v131
	v_fma_f32 v80, v80, v104, v132
	v_fma_f32 v81, v81, v104, v133
	v_cvt_pk_bf16_f32 v86, v86, v87
	v_cvt_pk_bf16_f32 v87, v88, v89
	v_cvt_pk_bf16_f32 v88, v78, v79
	v_cvt_pk_bf16_f32 v89, v80, v81
	v_permlane16_swap_b32_e32 v82, v74
	v_permlane16_swap_b32_e32 v83, v75
	v_permlane16_swap_b32_e32 v84, v76
	v_permlane16_swap_b32_e32 v85, v77
	v_cvt_f32_i32_e32 v82, v82
	v_cvt_f32_i32_e32 v83, v83
	v_cvt_f32_i32_e32 v84, v84
	v_cvt_f32_i32_e32 v85, v85
	v_cvt_f32_i32_e32 v74, v74
	v_cvt_f32_i32_e32 v75, v75
	v_cvt_f32_i32_e32 v76, v76
	v_cvt_f32_i32_e32 v77, v77
	s_waitcnt vmcnt(2)
	v_pk_mul_f32 v[82:83], v[82:83], v[114:115]
	v_pk_mul_f32 v[84:85], v[84:85], v[116:117]
	v_pk_mul_f32 v[74:75], v[74:75], v[118:119]
	v_pk_mul_f32 v[76:77], v[76:77], v[120:121]
	v_fma_f32 v82, v82, v105, v122
	v_fma_f32 v83, v83, v105, v123
	v_fma_f32 v84, v84, v105, v124
	v_fma_f32 v85, v85, v105, v125
	v_fma_f32 v74, v74, v105, v98
	v_fma_f32 v75, v75, v105, v99
	v_fma_f32 v76, v76, v105, v100
	v_fma_f32 v77, v77, v105, v101
	v_cvt_pk_bf16_f32 v82, v82, v83
	v_cvt_pk_bf16_f32 v83, v84, v85
	v_cvt_pk_bf16_f32 v84, v74, v75
	v_cvt_pk_bf16_f32 v85, v76, v77
	v_permlane16_swap_b32_e32 v70, v66
	v_permlane16_swap_b32_e32 v71, v67
	v_permlane16_swap_b32_e32 v72, v68
	v_permlane16_swap_b32_e32 v73, v69
	v_cvt_f32_i32_e32 v70, v70
	v_cvt_f32_i32_e32 v71, v71
	v_cvt_f32_i32_e32 v72, v72
	v_cvt_f32_i32_e32 v73, v73
	v_cvt_f32_i32_e32 v66, v66
	v_cvt_f32_i32_e32 v67, v67
	v_cvt_f32_i32_e32 v68, v68
	v_cvt_f32_i32_e32 v69, v69
	s_waitcnt vmcnt(0)
	v_pk_mul_f32 v[70:71], v[70:71], v[170:171]
	v_pk_mul_f32 v[72:73], v[72:73], v[172:173]
	v_pk_mul_f32 v[66:67], v[66:67], v[174:175]
	v_pk_mul_f32 v[68:69], v[68:69], v[176:177]
	v_fma_f32 v70, v70, v105, v178
	v_fma_f32 v71, v71, v105, v179
	v_fma_f32 v72, v72, v105, v180
	v_fma_f32 v73, v73, v105, v181
	v_fma_f32 v66, v66, v105, v182
	v_fma_f32 v67, v67, v105, v183
	v_fma_f32 v68, v68, v105, v184
	v_fma_f32 v69, v69, v105, v185
	v_cvt_pk_bf16_f32 v70, v70, v71
	v_cvt_pk_bf16_f32 v71, v72, v73
	v_cvt_pk_bf16_f32 v72, v66, v67
	v_cvt_pk_bf16_f32 v73, v68, v69
	v_add_u32_e32 v162, 0x200000, v161
	global_load_dwordx4 v[178:181], v162, s[58:59] offset:0
	global_load_dwordx4 v[182:185], v162, s[58:59] offset:16
	v_add_u32_e32 v231, 0x200000, v161
	global_load_dwordx4 v[186:189], v231, s[58:59] offset:512
	global_load_dwordx4 v[190:193], v231, s[58:59] offset:528
	v_add_u32_e32 v162, 0x240000, v161
	global_load_dwordx4 v[194:197], v162, s[58:59] offset:0
	global_load_dwordx4 v[198:201], v162, s[58:59] offset:16
	v_add_u32_e32 v231, 0x240000, v161
	global_load_dwordx4 v[202:205], v231, s[58:59] offset:512
	global_load_dwordx4 v[214:217], v231, s[58:59] offset:528
	v_add_u32_e32 v162, 0x280000, v161
	global_load_dwordx4 v[218:221], v162, s[58:59] offset:0
	global_load_dwordx4 v[222:225], v162, s[58:59] offset:16
	v_add_u32_e32 v231, 0x280000, v161
	global_load_dwordx4 v[138:141], v231, s[58:59] offset:512
	global_load_dwordx4 v[130:133], v231, s[58:59] offset:528
; __device__ __forceinline__ unsigned cvt_pk_bf16(float lo, float hi) { unsigned r; asm("v_cvt_pk_bf16_f32 %0, %1, %2" : "=v"(r) : "v"(lo), "v"(hi)); return r; }
;     __device__ __forceinline__ void operator()(const f32x4 (&acc)[2][2][4][2], const pg8::Unit& u, int wr, int wc, int fr, int fq) const {
;     ...
;         for (int am = 0; am < 4; ++am) { const int ai = am >> 1, m0 = 2 * (am & 1); f32x4 r[2][2][2];
; #pragma unroll
;             for (int mm = 0; mm < 2; ++mm) { const int row = row0 + ai * 128 + (m0 + mm) * 16; const float* xin = (row < MP ? xp + (size_t)row * DM : xs + (size_t)(row - MP) * DM) + col0;
; #pragma unroll
;                 for (int bj = 0; bj < 2; ++bj)
; #pragma unroll
;                     for (int n = 0; n < 2; ++n) r[mm][bj][n] = *(const f32x4*)(xin + bj * 128 + n * 16); }
; #pragma unroll
;             for (int mm = 0; mm < 2; ++mm) { const size_t off = (size_t)(row0 + ai * 128 + (m0 + mm) * 16) * DM + col0;
; #pragma unroll
;                 for (int bj = 0; bj < 2; ++bj)
; #pragma unroll
;                     for (int n = 0; n < 2; ++n) { const i32x4 q = __builtin_bit_cast(i32x4, acc[ai][bj][m0 + mm][n]);
;                         const f32x4 v = (f32x4){(float)q[0], (float)q[1], (float)q[2], (float)q[3]} * swv[bj][n] * sav[ai][m0 + mm] + r[mm][bj][n];
;                         u32x2 w; w.x = cvt_pk_bf16(v[0], v[1]); w.y = cvt_pk_bf16(v[2], v[3]); *(u32x2*)(X1 + off + bj * 128 + n * 16) = w; } } }
	v_add_u32_e32 v162, 0x2c0000, v161
	global_load_dwordx4 v[122:125], v162, s[58:59] offset:0
	global_load_dwordx4 v[98:101], v162, s[58:59] offset:16
	v_add_u32_e32 v231, 0x2c0000, v161
	global_load_dwordx4 v[90:93], v231, s[58:59] offset:512
	global_load_dwordx4 v[78:81], v231, s[58:59] offset:528
	v_mov_b32_e32 v162, v160
	global_store_dwordx4 v162, v[142:145], s[14:15] offset:0
	v_mov_b32_e32 v231, v160
	global_store_dwordx4 v231, v[134:137], s[14:15] offset:256
	v_add_u32_e32 v162, 0x20000, v160
	global_store_dwordx4 v162, v[126:129], s[14:15] offset:0
	v_add_u32_e32 v231, 0x20000, v160
	global_store_dwordx4 v231, v[110:113], s[14:15] offset:256
	v_add_u32_e32 v162, 0x40000, v160
	global_store_dwordx4 v162, v[94:97], s[14:15] offset:0
	v_add_u32_e32 v231, 0x40000, v160
	global_store_dwordx4 v231, v[86:89], s[14:15] offset:256
	v_add_u32_e32 v162, 0x60000, v160
	global_store_dwordx4 v162, v[82:85], s[14:15] offset:0
	v_add_u32_e32 v231, 0x60000, v160
	global_store_dwordx4 v231, v[70:73], s[14:15] offset:256
	v_permlane16_swap_b32_e32 v62, v58
	v_permlane16_swap_b32_e32 v63, v59
	v_permlane16_swap_b32_e32 v64, v60
	v_permlane16_swap_b32_e32 v65, v61
	v_cvt_f32_i32_e32 v62, v62
	v_cvt_f32_i32_e32 v63, v63
	v_cvt_f32_i32_e32 v64, v64
	v_cvt_f32_i32_e32 v65, v65
	v_cvt_f32_i32_e32 v58, v58
	v_cvt_f32_i32_e32 v59, v59
	v_cvt_f32_i32_e32 v60, v60
	v_cvt_f32_i32_e32 v61, v61
	s_waitcnt vmcnt(22)
	v_pk_mul_f32 v[62:63], v[62:63], v[114:115]
	v_pk_mul_f32 v[64:65], v[64:65], v[116:117]
	v_pk_mul_f32 v[58:59], v[58:59], v[118:119]
	v_pk_mul_f32 v[60:61], v[60:61], v[120:121]
	v_fma_f32 v62, v62, v106, v178
	v_fma_f32 v63, v63, v106, v179
	v_fma_f32 v64, v64, v106, v180
	v_fma_f32 v65, v65, v106, v181
	v_fma_f32 v58, v58, v106, v182
	v_fma_f32 v59, v59, v106, v183
	v_fma_f32 v60, v60, v106, v184
	v_fma_f32 v61, v61, v106, v185
	v_cvt_pk_bf16_f32 v62, v62, v63
	v_cvt_pk_bf16_f32 v63, v64, v65
	v_cvt_pk_bf16_f32 v64, v58, v59
	v_cvt_pk_bf16_f32 v65, v60, v61
	v_add_u32_e32 v162, 0x100000, v160
	global_store_dwordx4 v162, v[62:65], s[14:15] offset:0
	v_permlane16_swap_b32_e32 v54, v46
	v_permlane16_swap_b32_e32 v55, v47
	v_permlane16_swap_b32_e32 v56, v48
	v_permlane16_swap_b32_e32 v57, v49
	v_cvt_f32_i32_e32 v54, v54
	v_cvt_f32_i32_e32 v55, v55
	v_cvt_f32_i32_e32 v56, v56
	v_cvt_f32_i32_e32 v57, v57
	v_cvt_f32_i32_e32 v46, v46
	v_cvt_f32_i32_e32 v47, v47
	v_cvt_f32_i32_e32 v48, v48
	v_cvt_f32_i32_e32 v49, v49
	s_waitcnt vmcnt(21)
	v_pk_mul_f32 v[54:55], v[54:55], v[170:171]
	v_pk_mul_f32 v[56:57], v[56:57], v[172:173]
	v_pk_mul_f32 v[46:47], v[46:47], v[174:175]
	v_pk_mul_f32 v[48:49], v[48:49], v[176:177]
	v_fma_f32 v54, v54, v106, v186
	v_fma_f32 v55, v55, v106, v187
	v_fma_f32 v56, v56, v106, v188
	v_fma_f32 v57, v57, v106, v189
	v_fma_f32 v46, v46, v106, v190
	v_fma_f32 v47, v47, v106, v191
	v_fma_f32 v48, v48, v106, v192
	v_fma_f32 v49, v49, v106, v193
	v_cvt_pk_bf16_f32 v54, v54, v55
	v_cvt_pk_bf16_f32 v55, v56, v57
	v_cvt_pk_bf16_f32 v56, v46, v47
	v_cvt_pk_bf16_f32 v57, v48, v49
	v_add_u32_e32 v231, 0x100000, v160
	global_store_dwordx4 v231, v[54:57], s[14:15] offset:256
	v_permlane16_swap_b32_e32 v50, v42
	v_permlane16_swap_b32_e32 v51, v43
	v_permlane16_swap_b32_e32 v52, v44
	v_permlane16_swap_b32_e32 v53, v45
	v_cvt_f32_i32_e32 v50, v50
	v_cvt_f32_i32_e32 v51, v51
	v_cvt_f32_i32_e32 v52, v52
	v_cvt_f32_i32_e32 v53, v53
	v_cvt_f32_i32_e32 v42, v42
	v_cvt_f32_i32_e32 v43, v43
	v_cvt_f32_i32_e32 v44, v44
	v_cvt_f32_i32_e32 v45, v45
	s_waitcnt vmcnt(20)
	v_pk_mul_f32 v[50:51], v[50:51], v[114:115]
	v_pk_mul_f32 v[52:53], v[52:53], v[116:117]
	v_pk_mul_f32 v[42:43], v[42:43], v[118:119]
	v_pk_mul_f32 v[44:45], v[44:45], v[120:121]
	v_fma_f32 v50, v50, v107, v194
	v_fma_f32 v51, v51, v107, v195
	v_fma_f32 v52, v52, v107, v196
	v_fma_f32 v53, v53, v107, v197
	v_fma_f32 v42, v42, v107, v198
	v_fma_f32 v43, v43, v107, v199
	v_fma_f32 v44, v44, v107, v200
	v_fma_f32 v45, v45, v107, v201
	v_cvt_pk_bf16_f32 v50, v50, v51
	v_cvt_pk_bf16_f32 v51, v52, v53
	v_cvt_pk_bf16_f32 v52, v42, v43
	v_cvt_pk_bf16_f32 v53, v44, v45
	v_add_u32_e32 v162, 0x120000, v160
	global_store_dwordx4 v162, v[50:53], s[14:15] offset:0
	v_permlane16_swap_b32_e32 v38, v34
	v_permlane16_swap_b32_e32 v39, v35
	v_permlane16_swap_b32_e32 v40, v36
	v_permlane16_swap_b32_e32 v41, v37
	v_cvt_f32_i32_e32 v38, v38
	v_cvt_f32_i32_e32 v39, v39
	v_cvt_f32_i32_e32 v40, v40
	v_cvt_f32_i32_e32 v41, v41
	v_cvt_f32_i32_e32 v34, v34
	v_cvt_f32_i32_e32 v35, v35
	v_cvt_f32_i32_e32 v36, v36
	v_cvt_f32_i32_e32 v37, v37
	s_waitcnt vmcnt(19)
; __device__ __forceinline__ unsigned cvt_pk_bf16(float lo, float hi) { unsigned r; asm("v_cvt_pk_bf16_f32 %0, %1, %2" : "=v"(r) : "v"(lo), "v"(hi)); return r; }
; #define PG8_BAR __builtin_amdgcn_s_barrier()
; template <class Epi, class Geom, class Sched, bool ALIGN_EPI, bool I8 = false>
; __device__ __forceinline__ void gemm_phase(LAS unsigned char* lds, const Gemm g, const Sched& S, const Epi& E) {
;     ...
;         if (!has_next) break;
; #pragma unroll
;         for (int a = 0; a < 2; ++a)
; #pragma unroll
;             for (int b = 0; b < 2; ++b)
; #pragma unroll
;                 for (int m = 0; m < 4; ++m)
; #pragma unroll
;                     for (int n = 0; n < 2; ++n) acc[a][b][m][n] = (f32x4){0.f, 0.f, 0.f, 0.f};
;         cur = nxt; cA = nA; cB = nB; ++ui;
;         if constexpr (ALIGN_EPI) { if (wr == 1) PG8_BAR; }
;     __device__ __forceinline__ void operator()(const f32x4 (&acc)[2][2][4][2], const pg8::Unit& u, int wr, int wc, int fr, int fq) const {
;     ...
;         for (int am = 0; am < 4; ++am) { const int ai = am >> 1, m0 = 2 * (am & 1); f32x4 r[2][2][2];
; #pragma unroll
;             for (int mm = 0; mm < 2; ++mm) { const int row = row0 + ai * 128 + (m0 + mm) * 16; const float* xin = (row < MP ? xp + (size_t)row * DM : xs + (size_t)(row - MP) * DM) + col0;
; #pragma unroll
;                 for (int bj = 0; bj < 2; ++bj)
; #pragma unroll
;                     for (int n = 0; n < 2; ++n) r[mm][bj][n] = *(const f32x4*)(xin + bj * 128 + n * 16); }
; #pragma unroll
;             for (int mm = 0; mm < 2; ++mm) { const size_t off = (size_t)(row0 + ai * 128 + (m0 + mm) * 16) * DM + col0;
; #pragma unroll
;                 for (int bj = 0; bj < 2; ++bj)
; #pragma unroll
;                     for (int n = 0; n < 2; ++n) { const i32x4 q = __builtin_bit_cast(i32x4, acc[ai][bj][m0 + mm][n]);
;                         const f32x4 v = (f32x4){(float)q[0], (float)q[1], (float)q[2], (float)q[3]} * swv[bj][n] * sav[ai][m0 + mm] + r[mm][bj][n];
;                         u32x2 w; w.x = cvt_pk_bf16(v[0], v[1]); w.y = cvt_pk_bf16(v[2], v[3]); *(u32x2*)(X1 + off + bj * 128 + n * 16) = w; } } }
	v_pk_mul_f32 v[38:39], v[38:39], v[170:171]
	v_pk_mul_f32 v[40:41], v[40:41], v[172:173]
	v_pk_mul_f32 v[34:35], v[34:35], v[174:175]
	v_pk_mul_f32 v[36:37], v[36:37], v[176:177]
	v_fma_f32 v38, v38, v107, v202
	v_fma_f32 v39, v39, v107, v203
	v_fma_f32 v40, v40, v107, v204
	v_fma_f32 v41, v41, v107, v205
	v_fma_f32 v34, v34, v107, v214
	v_fma_f32 v35, v35, v107, v215
	v_fma_f32 v36, v36, v107, v216
	v_fma_f32 v37, v37, v107, v217
	v_cvt_pk_bf16_f32 v38, v38, v39
	v_cvt_pk_bf16_f32 v39, v40, v41
	v_cvt_pk_bf16_f32 v40, v34, v35
	v_cvt_pk_bf16_f32 v41, v36, v37
	v_add_u32_e32 v231, 0x120000, v160
	global_store_dwordx4 v231, v[38:41], s[14:15] offset:256
	v_permlane16_swap_b32_e32 v30, v26
	v_permlane16_swap_b32_e32 v31, v27
	v_permlane16_swap_b32_e32 v32, v28
	v_permlane16_swap_b32_e32 v33, v29
	v_cvt_f32_i32_e32 v30, v30
	v_cvt_f32_i32_e32 v31, v31
	v_cvt_f32_i32_e32 v32, v32
	v_cvt_f32_i32_e32 v33, v33
	v_cvt_f32_i32_e32 v26, v26
	v_cvt_f32_i32_e32 v27, v27
	v_cvt_f32_i32_e32 v28, v28
	v_cvt_f32_i32_e32 v29, v29
	s_waitcnt vmcnt(18)
	v_pk_mul_f32 v[30:31], v[30:31], v[114:115]
	v_pk_mul_f32 v[32:33], v[32:33], v[116:117]
	v_pk_mul_f32 v[26:27], v[26:27], v[118:119]
	v_pk_mul_f32 v[28:29], v[28:29], v[120:121]
	v_fma_f32 v30, v30, v108, v218
	v_fma_f32 v31, v31, v108, v219
	v_fma_f32 v32, v32, v108, v220
	v_fma_f32 v33, v33, v108, v221
	v_fma_f32 v26, v26, v108, v222
	v_fma_f32 v27, v27, v108, v223
	v_fma_f32 v28, v28, v108, v224
	v_fma_f32 v29, v29, v108, v225
	v_cvt_pk_bf16_f32 v30, v30, v31
	v_cvt_pk_bf16_f32 v31, v32, v33
	v_cvt_pk_bf16_f32 v32, v26, v27
	v_cvt_pk_bf16_f32 v33, v28, v29
	v_add_u32_e32 v162, 0x140000, v160
	global_store_dwordx4 v162, v[30:33], s[14:15] offset:0
	v_permlane16_swap_b32_e32 v22, v14
	v_permlane16_swap_b32_e32 v23, v15
	v_permlane16_swap_b32_e32 v24, v16
	v_permlane16_swap_b32_e32 v25, v17
	v_cvt_f32_i32_e32 v22, v22
	v_cvt_f32_i32_e32 v23, v23
	v_cvt_f32_i32_e32 v24, v24
	v_cvt_f32_i32_e32 v25, v25
	v_cvt_f32_i32_e32 v14, v14
	v_cvt_f32_i32_e32 v15, v15
	v_cvt_f32_i32_e32 v16, v16
	v_cvt_f32_i32_e32 v17, v17
	s_waitcnt vmcnt(17)
	v_pk_mul_f32 v[22:23], v[22:23], v[170:171]
	v_pk_mul_f32 v[24:25], v[24:25], v[172:173]
	v_pk_mul_f32 v[14:15], v[14:15], v[174:175]
	v_pk_mul_f32 v[16:17], v[16:17], v[176:177]
	v_fma_f32 v22, v22, v108, v138
	v_fma_f32 v23, v23, v108, v139
	v_fma_f32 v24, v24, v108, v140
	v_fma_f32 v25, v25, v108, v141
	v_fma_f32 v14, v14, v108, v130
	v_fma_f32 v15, v15, v108, v131
	v_fma_f32 v16, v16, v108, v132
	v_fma_f32 v17, v17, v108, v133
	v_cvt_pk_bf16_f32 v22, v22, v23
	v_cvt_pk_bf16_f32 v23, v24, v25
	v_cvt_pk_bf16_f32 v24, v14, v15
	v_cvt_pk_bf16_f32 v25, v16, v17
	v_add_u32_e32 v231, 0x140000, v160
	global_store_dwordx4 v231, v[22:25], s[14:15] offset:256
	v_permlane16_swap_b32_e32 v18, v10
	v_permlane16_swap_b32_e32 v19, v11
	v_permlane16_swap_b32_e32 v20, v12
	v_permlane16_swap_b32_e32 v21, v13
	v_cvt_f32_i32_e32 v18, v18
	v_cvt_f32_i32_e32 v19, v19
	v_cvt_f32_i32_e32 v20, v20
	v_cvt_f32_i32_e32 v21, v21
	v_cvt_f32_i32_e32 v10, v10
	v_cvt_f32_i32_e32 v11, v11
	v_cvt_f32_i32_e32 v12, v12
	v_cvt_f32_i32_e32 v13, v13
	s_waitcnt vmcnt(16)
	v_pk_mul_f32 v[18:19], v[18:19], v[114:115]
	v_pk_mul_f32 v[20:21], v[20:21], v[116:117]
	v_pk_mul_f32 v[10:11], v[10:11], v[118:119]
	v_pk_mul_f32 v[12:13], v[12:13], v[120:121]
	v_fma_f32 v18, v18, v109, v122
	v_fma_f32 v19, v19, v109, v123
	v_fma_f32 v20, v20, v109, v124
	v_fma_f32 v21, v21, v109, v125
	v_fma_f32 v10, v10, v109, v98
	v_fma_f32 v11, v11, v109, v99
	v_fma_f32 v12, v12, v109, v100
	v_fma_f32 v13, v13, v109, v101
	v_cvt_pk_bf16_f32 v18, v18, v19
	v_cvt_pk_bf16_f32 v19, v20, v21
	v_cvt_pk_bf16_f32 v20, v10, v11
	v_cvt_pk_bf16_f32 v21, v12, v13
	v_add_u32_e32 v162, 0x160000, v160
	global_store_dwordx4 v162, v[18:21], s[14:15] offset:0
	v_permlane16_swap_b32_e32 v6, v2
	v_permlane16_swap_b32_e32 v7, v3
	v_permlane16_swap_b32_e32 v8, v4
	v_permlane16_swap_b32_e32 v9, v5
	v_cvt_f32_i32_e32 v6, v6
	v_cvt_f32_i32_e32 v7, v7
	v_cvt_f32_i32_e32 v8, v8
	v_cvt_f32_i32_e32 v9, v9
	v_cvt_f32_i32_e32 v2, v2
	v_cvt_f32_i32_e32 v3, v3
	v_cvt_f32_i32_e32 v4, v4
	v_cvt_f32_i32_e32 v5, v5
	s_waitcnt vmcnt(15)
	v_pk_mul_f32 v[6:7], v[6:7], v[170:171]
	v_pk_mul_f32 v[8:9], v[8:9], v[172:173]
	v_pk_mul_f32 v[2:3], v[2:3], v[174:175]
	v_pk_mul_f32 v[4:5], v[4:5], v[176:177]
	v_fma_f32 v6, v6, v109, v90
	v_fma_f32 v7, v7, v109, v91
	v_fma_f32 v8, v8, v109, v92
	v_fma_f32 v9, v9, v109, v93
	v_fma_f32 v2, v2, v109, v78
	v_fma_f32 v3, v3, v109, v79
	v_fma_f32 v4, v4, v109, v80
	v_fma_f32 v5, v5, v109, v81
	v_cvt_pk_bf16_f32 v6, v6, v7
	v_cvt_pk_bf16_f32 v7, v8, v9
	v_cvt_pk_bf16_f32 v8, v2, v3
	v_cvt_pk_bf16_f32 v9, v4, v5
	v_add_u32_e32 v231, 0x160000, v160
	global_store_dwordx4 v231, v[6:9], s[14:15] offset:256
	s_andn2_b64 vcc, exec, s[4:5]
	s_mov_b64 s[4:5], -1
	s_cbranch_vccnz .LBB0_2227
	s_andn2_b64 vcc, exec, s[12:13]
	s_cbranch_vccnz .LBB0_2226
	s_barrier
	s_branch .LBB0_2226

; __device__ __forceinline__ unsigned cvt_pk_bf16(float lo, float hi) { unsigned r; asm("v_cvt_pk_bf16_f32 %0, %1, %2" : "=v"(r) : "v"(lo), "v"(hi)); return r; }
;     __device__ __forceinline__ void operator()(const f32x4 (&acc)[2][2][4][2], const pg8::Unit& u, int wr, int wc, int fr, int fq) const {
;         bf16_t* base = P + ((size_t)(u.tl * 8 + u.ks) << 16) + (size_t)(wr * 64 + fr) * 256 + wc * 32 + 4 * fq;
;         const int row0 = u.pm * 256 + wr * 64 + fr, col0 = u.pn * 256 + wc * 32 + 4 * fq;
;         f32x4 swv[2][2];
; #pragma unroll
;         for (int bj = 0; bj < 2; ++bj)
; #pragma unroll
;             for (int n = 0; n < 2; ++n) swv[bj][n] = *(const f32x4*)(sw + col0 + bj * 128 + n * 16);
; #pragma unroll
;         for (int ai = 0; ai < 2; ++ai)
; #pragma unroll
;             for (int m = 0; m < 4; ++m) { const float sav = sa[row0 + ai * 128 + m * 16];
; #pragma unroll
;                 for (int bj = 0; bj < 2; ++bj)
; #pragma unroll
;                     for (int n = 0; n < 2; ++n) { const i32x4 q = __builtin_bit_cast(i32x4, acc[ai][bj][m][n]);
;                         const f32x4 v = (f32x4){(float)q[0], (float)q[1], (float)q[2], (float)q[3]} * swv[bj][n] * sav;
;                         u32x2 o; o.x = cvt_pk_bf16(v[0], v[1]); o.y = cvt_pk_bf16(v[2], v[3]);
;                         *(u32x2*)(base + (size_t)(ai * 128 + m * 16) * 256 + bj * 128 + n * 16) = o; } }
;     }
.LBB0_2246:
	v_lshl_add_u32 v160, s31, 8, v150
	v_and_b32_e32 v161, 1, v235
	v_mul_u32_u24_e32 v161, 12, v161
	v_lshl_add_u32 v161, v235, 2, v161
	v_add_u32_e32 v161, s3, v161
	v_lshlrev_b32_e32 v164, 9, v150
	v_lshl_add_u32 v164, v161, 1, v164
	v_lshl_or_b32 v161, s35, 8, v161
	v_lshlrev_b32_e32 v163, 2, v161
	v_mbcnt_lo_u32_b32 v162, -1, 0
	v_mbcnt_hi_u32_b32 v162, -1, v162
	v_and_b32_e32 v194, 64, v150
	v_add_u32_e32 v162, v162, v194
	v_lshl_add_u32 v162, s31, 8, v162
	v_lshlrev_b32_e32 v162, 2, v162
	v_and_b32_e32 v194, 15, v150
	v_lshlrev_b32_e32 v194, 2, v194
	global_load_dword v192, v162, s[6:7]
	global_load_dword v193, v162, s[6:7] offset:512
	global_load_dwordx4 v[176:179], v163, s[8:9] offset:0
	global_load_dwordx4 v[180:183], v163, s[8:9] offset:16
	global_load_dwordx4 v[184:187], v163, s[8:9] offset:512
	global_load_dwordx4 v[188:191], v163, s[8:9] offset:528
	s_lshl_b32 s4, s30, 3
	s_add_i32 s4, s4, s2
	s_ashr_i32 s5, s4, 31
	s_lshl_b64 s[4:5], s[4:5], 17
	s_add_u32 s4, s86, s4
	s_addc_u32 s5, s87, s5
	s_add_u32 s4, s4, 0x2a50f000
	s_addc_u32 s5, s5, 0
	v_permlane16_swap_b32_e32 v142, v122
	v_permlane16_swap_b32_e32 v143, v123
	v_permlane16_swap_b32_e32 v144, v124
	v_permlane16_swap_b32_e32 v145, v125
	v_cvt_f32_i32_e32 v142, v142
	v_cvt_f32_i32_e32 v143, v143
	v_cvt_f32_i32_e32 v144, v144
	v_cvt_f32_i32_e32 v145, v145
	v_cvt_f32_i32_e32 v122, v122
	v_cvt_f32_i32_e32 v123, v123
	v_cvt_f32_i32_e32 v124, v124
	v_cvt_f32_i32_e32 v125, v125
	s_waitcnt vmcnt(0)
	ds_bpermute_b32 v168, v194, v192
	ds_bpermute_b32 v169, v194, v192 offset:64
	ds_bpermute_b32 v170, v194, v192 offset:128
	ds_bpermute_b32 v171, v194, v192 offset:192
	ds_bpermute_b32 v172, v194, v193
	ds_bpermute_b32 v173, v194, v193 offset:64
	ds_bpermute_b32 v174, v194, v193 offset:128
	ds_bpermute_b32 v175, v194, v193 offset:192
	s_waitcnt lgkmcnt(0)
	v_pk_mul_f32 v[142:143], v[142:143], v[176:177]
	v_pk_mul_f32 v[144:145], v[144:145], v[178:179]
	v_pk_mul_f32 v[122:123], v[122:123], v[180:181]
	v_pk_mul_f32 v[124:125], v[124:125], v[182:183]
	v_mul_f32_e32 v142, v142, v168
	v_mul_f32_e32 v143, v143, v168
	v_mul_f32_e32 v144, v144, v168
	v_mul_f32_e32 v145, v145, v168
	v_mul_f32_e32 v122, v122, v168
	v_mul_f32_e32 v123, v123, v168
	v_mul_f32_e32 v124, v124, v168
	v_mul_f32_e32 v125, v125, v168
	v_cvt_pk_bf16_f32 v142, v142, v143
	v_cvt_pk_bf16_f32 v143, v144, v145
	v_cvt_pk_bf16_f32 v144, v122, v123
	v_cvt_pk_bf16_f32 v145, v124, v125
	v_mov_b32_e32 v165, v164
	global_store_dwordx4 v165, v[142:145], s[4:5] offset:0
	v_permlane16_swap_b32_e32 v118, v114
	v_permlane16_swap_b32_e32 v119, v115
	v_permlane16_swap_b32_e32 v120, v116
	v_permlane16_swap_b32_e32 v121, v117
	v_cvt_f32_i32_e32 v118, v118
	v_cvt_f32_i32_e32 v119, v119
	v_cvt_f32_i32_e32 v120, v120
	v_cvt_f32_i32_e32 v121, v121
	v_cvt_f32_i32_e32 v114, v114
	v_cvt_f32_i32_e32 v115, v115
	v_cvt_f32_i32_e32 v116, v116
	v_cvt_f32_i32_e32 v117, v117
	v_pk_mul_f32 v[118:119], v[118:119], v[184:185]
	v_pk_mul_f32 v[120:121], v[120:121], v[186:187]
	v_pk_mul_f32 v[114:115], v[114:115], v[188:189]
	v_pk_mul_f32 v[116:117], v[116:117], v[190:191]
	v_mul_f32_e32 v118, v118, v168
	v_mul_f32_e32 v119, v119, v168
	v_mul_f32_e32 v120, v120, v168
	v_mul_f32_e32 v121, v121, v168
	v_mul_f32_e32 v114, v114, v168
	v_mul_f32_e32 v115, v115, v168
	v_mul_f32_e32 v116, v116, v168
	v_mul_f32_e32 v117, v117, v168
	v_cvt_pk_bf16_f32 v118, v118, v119
	v_cvt_pk_bf16_f32 v119, v120, v121
	v_cvt_pk_bf16_f32 v120, v114, v115
	v_cvt_pk_bf16_f32 v121, v116, v117
	v_mov_b32_e32 v166, v164
	global_store_dwordx4 v166, v[118:121], s[4:5] offset:256
	v_permlane16_swap_b32_e32 v110, v106
	v_permlane16_swap_b32_e32 v111, v107
	v_permlane16_swap_b32_e32 v112, v108
	v_permlane16_swap_b32_e32 v113, v109
	v_cvt_f32_i32_e32 v110, v110
	v_cvt_f32_i32_e32 v111, v111
	v_cvt_f32_i32_e32 v112, v112
	v_cvt_f32_i32_e32 v113, v113
	v_cvt_f32_i32_e32 v106, v106
	v_cvt_f32_i32_e32 v107, v107
	v_cvt_f32_i32_e32 v108, v108
	v_cvt_f32_i32_e32 v109, v109
	v_pk_mul_f32 v[110:111], v[110:111], v[176:177]
	v_pk_mul_f32 v[112:113], v[112:113], v[178:179]
	v_pk_mul_f32 v[106:107], v[106:107], v[180:181]
	v_pk_mul_f32 v[108:109], v[108:109], v[182:183]
	v_mul_f32_e32 v110, v110, v169
	v_mul_f32_e32 v111, v111, v169
	v_mul_f32_e32 v112, v112, v169
	v_mul_f32_e32 v113, v113, v169
	v_mul_f32_e32 v106, v106, v169
	v_mul_f32_e32 v107, v107, v169
	v_mul_f32_e32 v108, v108, v169
	v_mul_f32_e32 v109, v109, v169
	v_cvt_pk_bf16_f32 v110, v110, v111
	v_cvt_pk_bf16_f32 v111, v112, v113
	v_cvt_pk_bf16_f32 v112, v106, v107
	v_cvt_pk_bf16_f32 v113, v108, v109
	v_add_u32_e32 v165, 0x2000, v164
	global_store_dwordx4 v165, v[110:113], s[4:5] offset:0
	v_permlane16_swap_b32_e32 v102, v98
	v_permlane16_swap_b32_e32 v103, v99
	v_permlane16_swap_b32_e32 v104, v100
	v_permlane16_swap_b32_e32 v105, v101
	v_cvt_f32_i32_e32 v102, v102
	v_cvt_f32_i32_e32 v103, v103
	v_cvt_f32_i32_e32 v104, v104
	v_cvt_f32_i32_e32 v105, v105
	v_cvt_f32_i32_e32 v98, v98
	v_cvt_f32_i32_e32 v99, v99
	v_cvt_f32_i32_e32 v100, v100
	v_cvt_f32_i32_e32 v101, v101
	v_pk_mul_f32 v[102:103], v[102:103], v[184:185]
	v_pk_mul_f32 v[104:105], v[104:105], v[186:187]
	v_pk_mul_f32 v[98:99], v[98:99], v[188:189]
	v_pk_mul_f32 v[100:101], v[100:101], v[190:191]
	v_mul_f32_e32 v102, v102, v169
	v_mul_f32_e32 v103, v103, v169
	v_mul_f32_e32 v104, v104, v169
	v_mul_f32_e32 v105, v105, v169
	v_mul_f32_e32 v98, v98, v169
	v_mul_f32_e32 v99, v99, v169
	v_mul_f32_e32 v100, v100, v169
	v_mul_f32_e32 v101, v101, v169
	v_cvt_pk_bf16_f32 v102, v102, v103
	v_cvt_pk_bf16_f32 v103, v104, v105
	v_cvt_pk_bf16_f32 v104, v98, v99
	v_cvt_pk_bf16_f32 v105, v100, v101
; __device__ __forceinline__ unsigned cvt_pk_bf16(float lo, float hi) { unsigned r; asm("v_cvt_pk_bf16_f32 %0, %1, %2" : "=v"(r) : "v"(lo), "v"(hi)); return r; }
;     __device__ __forceinline__ void operator()(const f32x4 (&acc)[2][2][4][2], const pg8::Unit& u, int wr, int wc, int fr, int fq) const {
;     ...
;         for (int ai = 0; ai < 2; ++ai)
; #pragma unroll
;             for (int m = 0; m < 4; ++m) { const float sav = sa[row0 + ai * 128 + m * 16];
; #pragma unroll
;                 for (int bj = 0; bj < 2; ++bj)
; #pragma unroll
;                     for (int n = 0; n < 2; ++n) { const i32x4 q = __builtin_bit_cast(i32x4, acc[ai][bj][m][n]);
;                         const f32x4 v = (f32x4){(float)q[0], (float)q[1], (float)q[2], (float)q[3]} * swv[bj][n] * sav;
;                         u32x2 o; o.x = cvt_pk_bf16(v[0], v[1]); o.y = cvt_pk_bf16(v[2], v[3]);
;                         *(u32x2*)(base + (size_t)(ai * 128 + m * 16) * 256 + bj * 128 + n * 16) = o; } }
	v_add_u32_e32 v166, 0x2000, v164
	global_store_dwordx4 v166, v[102:105], s[4:5] offset:256
	v_permlane16_swap_b32_e32 v94, v90
	v_permlane16_swap_b32_e32 v95, v91
	v_permlane16_swap_b32_e32 v96, v92
	v_permlane16_swap_b32_e32 v97, v93
	v_cvt_f32_i32_e32 v94, v94
	v_cvt_f32_i32_e32 v95, v95
	v_cvt_f32_i32_e32 v96, v96
	v_cvt_f32_i32_e32 v97, v97
	v_cvt_f32_i32_e32 v90, v90
	v_cvt_f32_i32_e32 v91, v91
	v_cvt_f32_i32_e32 v92, v92
	v_cvt_f32_i32_e32 v93, v93
	v_pk_mul_f32 v[94:95], v[94:95], v[176:177]
	v_pk_mul_f32 v[96:97], v[96:97], v[178:179]
	v_pk_mul_f32 v[90:91], v[90:91], v[180:181]
	v_pk_mul_f32 v[92:93], v[92:93], v[182:183]
	v_mul_f32_e32 v94, v94, v170
	v_mul_f32_e32 v95, v95, v170
	v_mul_f32_e32 v96, v96, v170
	v_mul_f32_e32 v97, v97, v170
	v_mul_f32_e32 v90, v90, v170
	v_mul_f32_e32 v91, v91, v170
	v_mul_f32_e32 v92, v92, v170
	v_mul_f32_e32 v93, v93, v170
	v_cvt_pk_bf16_f32 v94, v94, v95
	v_cvt_pk_bf16_f32 v95, v96, v97
	v_cvt_pk_bf16_f32 v96, v90, v91
	v_cvt_pk_bf16_f32 v97, v92, v93
	v_add_u32_e32 v165, 0x4000, v164
	global_store_dwordx4 v165, v[94:97], s[4:5] offset:0
	v_permlane16_swap_b32_e32 v86, v82
	v_permlane16_swap_b32_e32 v87, v83
	v_permlane16_swap_b32_e32 v88, v84
	v_permlane16_swap_b32_e32 v89, v85
	v_cvt_f32_i32_e32 v86, v86
	v_cvt_f32_i32_e32 v87, v87
	v_cvt_f32_i32_e32 v88, v88
	v_cvt_f32_i32_e32 v89, v89
	v_cvt_f32_i32_e32 v82, v82
	v_cvt_f32_i32_e32 v83, v83
	v_cvt_f32_i32_e32 v84, v84
	v_cvt_f32_i32_e32 v85, v85
	v_pk_mul_f32 v[86:87], v[86:87], v[184:185]
	v_pk_mul_f32 v[88:89], v[88:89], v[186:187]
	v_pk_mul_f32 v[82:83], v[82:83], v[188:189]
	v_pk_mul_f32 v[84:85], v[84:85], v[190:191]
	v_mul_f32_e32 v86, v86, v170
	v_mul_f32_e32 v87, v87, v170
	v_mul_f32_e32 v88, v88, v170
	v_mul_f32_e32 v89, v89, v170
	v_mul_f32_e32 v82, v82, v170
	v_mul_f32_e32 v83, v83, v170
	v_mul_f32_e32 v84, v84, v170
	v_mul_f32_e32 v85, v85, v170
	v_cvt_pk_bf16_f32 v86, v86, v87
	v_cvt_pk_bf16_f32 v87, v88, v89
	v_cvt_pk_bf16_f32 v88, v82, v83
	v_cvt_pk_bf16_f32 v89, v84, v85
	v_add_u32_e32 v166, 0x4000, v164
	global_store_dwordx4 v166, v[86:89], s[4:5] offset:256
	v_permlane16_swap_b32_e32 v78, v74
	v_permlane16_swap_b32_e32 v79, v75
	v_permlane16_swap_b32_e32 v80, v76
	v_permlane16_swap_b32_e32 v81, v77
	v_cvt_f32_i32_e32 v78, v78
	v_cvt_f32_i32_e32 v79, v79
	v_cvt_f32_i32_e32 v80, v80
	v_cvt_f32_i32_e32 v81, v81
	v_cvt_f32_i32_e32 v74, v74
	v_cvt_f32_i32_e32 v75, v75
	v_cvt_f32_i32_e32 v76, v76
	v_cvt_f32_i32_e32 v77, v77
	v_pk_mul_f32 v[78:79], v[78:79], v[176:177]
	v_pk_mul_f32 v[80:81], v[80:81], v[178:179]
	v_pk_mul_f32 v[74:75], v[74:75], v[180:181]
	v_pk_mul_f32 v[76:77], v[76:77], v[182:183]
	v_mul_f32_e32 v78, v78, v171
	v_mul_f32_e32 v79, v79, v171
	v_mul_f32_e32 v80, v80, v171
	v_mul_f32_e32 v81, v81, v171
	v_mul_f32_e32 v74, v74, v171
	v_mul_f32_e32 v75, v75, v171
	v_mul_f32_e32 v76, v76, v171
	v_mul_f32_e32 v77, v77, v171
	v_cvt_pk_bf16_f32 v78, v78, v79
	v_cvt_pk_bf16_f32 v79, v80, v81
	v_cvt_pk_bf16_f32 v80, v74, v75
	v_cvt_pk_bf16_f32 v81, v76, v77
	v_add_u32_e32 v165, 0x6000, v164
	global_store_dwordx4 v165, v[78:81], s[4:5] offset:0
	v_permlane16_swap_b32_e32 v70, v66
	v_permlane16_swap_b32_e32 v71, v67
	v_permlane16_swap_b32_e32 v72, v68
	v_permlane16_swap_b32_e32 v73, v69
	v_cvt_f32_i32_e32 v70, v70
	v_cvt_f32_i32_e32 v71, v71
	v_cvt_f32_i32_e32 v72, v72
	v_cvt_f32_i32_e32 v73, v73
	v_cvt_f32_i32_e32 v66, v66
	v_cvt_f32_i32_e32 v67, v67
	v_cvt_f32_i32_e32 v68, v68
	v_cvt_f32_i32_e32 v69, v69
	v_pk_mul_f32 v[70:71], v[70:71], v[184:185]
	v_pk_mul_f32 v[72:73], v[72:73], v[186:187]
	v_pk_mul_f32 v[66:67], v[66:67], v[188:189]
	v_pk_mul_f32 v[68:69], v[68:69], v[190:191]
	v_mul_f32_e32 v70, v70, v171
	v_mul_f32_e32 v71, v71, v171
	v_mul_f32_e32 v72, v72, v171
	v_mul_f32_e32 v73, v73, v171
	v_mul_f32_e32 v66, v66, v171
	v_mul_f32_e32 v67, v67, v171
	v_mul_f32_e32 v68, v68, v171
	v_mul_f32_e32 v69, v69, v171
	v_cvt_pk_bf16_f32 v70, v70, v71
	v_cvt_pk_bf16_f32 v71, v72, v73
	v_cvt_pk_bf16_f32 v72, v66, v67
	v_cvt_pk_bf16_f32 v73, v68, v69
	v_add_u32_e32 v166, 0x6000, v164
	global_store_dwordx4 v166, v[70:73], s[4:5] offset:256
	v_permlane16_swap_b32_e32 v62, v58
	v_permlane16_swap_b32_e32 v63, v59
	v_permlane16_swap_b32_e32 v64, v60
	v_permlane16_swap_b32_e32 v65, v61
	v_cvt_f32_i32_e32 v62, v62
	v_cvt_f32_i32_e32 v63, v63
	v_cvt_f32_i32_e32 v64, v64
	v_cvt_f32_i32_e32 v65, v65
	v_cvt_f32_i32_e32 v58, v58
	v_cvt_f32_i32_e32 v59, v59
	v_cvt_f32_i32_e32 v60, v60
	v_cvt_f32_i32_e32 v61, v61
	v_pk_mul_f32 v[62:63], v[62:63], v[176:177]
	v_pk_mul_f32 v[64:65], v[64:65], v[178:179]
	v_pk_mul_f32 v[58:59], v[58:59], v[180:181]
	v_pk_mul_f32 v[60:61], v[60:61], v[182:183]
	v_mul_f32_e32 v62, v62, v172
	v_mul_f32_e32 v63, v63, v172
	v_mul_f32_e32 v64, v64, v172
	v_mul_f32_e32 v65, v65, v172
	v_mul_f32_e32 v58, v58, v172
	v_mul_f32_e32 v59, v59, v172
	v_mul_f32_e32 v60, v60, v172
	v_mul_f32_e32 v61, v61, v172
	v_cvt_pk_bf16_f32 v62, v62, v63
	v_cvt_pk_bf16_f32 v63, v64, v65
	v_cvt_pk_bf16_f32 v64, v58, v59
	v_cvt_pk_bf16_f32 v65, v60, v61
	v_add_u32_e32 v165, 0x10000, v164
	global_store_dwordx4 v165, v[62:65], s[4:5] offset:0
	v_permlane16_swap_b32_e32 v54, v50
	v_permlane16_swap_b32_e32 v55, v51
	v_permlane16_swap_b32_e32 v56, v52
	v_permlane16_swap_b32_e32 v57, v53
	v_cvt_f32_i32_e32 v54, v54
	v_cvt_f32_i32_e32 v55, v55
	v_cvt_f32_i32_e32 v56, v56
	v_cvt_f32_i32_e32 v57, v57
	v_cvt_f32_i32_e32 v50, v50
	v_cvt_f32_i32_e32 v51, v51
	v_cvt_f32_i32_e32 v52, v52
	v_cvt_f32_i32_e32 v53, v53
	v_pk_mul_f32 v[54:55], v[54:55], v[184:185]
	v_pk_mul_f32 v[56:57], v[56:57], v[186:187]
	v_pk_mul_f32 v[50:51], v[50:51], v[188:189]
; __device__ __forceinline__ unsigned cvt_pk_bf16(float lo, float hi) { unsigned r; asm("v_cvt_pk_bf16_f32 %0, %1, %2" : "=v"(r) : "v"(lo), "v"(hi)); return r; }
; #define PG8_WAIT_V(n) asm volatile("s_waitcnt vmcnt(" #n ")" ::: "memory")
; #define PG8_BAR __builtin_amdgcn_s_barrier()
; template <class Epi, class Geom, class Sched, bool ALIGN_EPI, bool I8 = false>
; __device__ __forceinline__ void gemm_phase(LAS unsigned char* lds, const Gemm g, const Sched& S, const Epi& E) {
;     ...
;     PG8_WAIT_V(0);
;     if constexpr (!ALIGN_EPI) { if (wr == 0) PG8_BAR; }
;     PG8_BAR;
;     __device__ __forceinline__ void operator()(const f32x4 (&acc)[2][2][4][2], const pg8::Unit& u, int wr, int wc, int fr, int fq) const {
;     ...
;                 for (int bj = 0; bj < 2; ++bj)
; #pragma unroll
;                     for (int n = 0; n < 2; ++n) { const i32x4 q = __builtin_bit_cast(i32x4, acc[ai][bj][m][n]);
;                         const f32x4 v = (f32x4){(float)q[0], (float)q[1], (float)q[2], (float)q[3]} * swv[bj][n] * sav;
;                         u32x2 o; o.x = cvt_pk_bf16(v[0], v[1]); o.y = cvt_pk_bf16(v[2], v[3]);
;                         *(u32x2*)(base + (size_t)(ai * 128 + m * 16) * 256 + bj * 128 + n * 16) = o; } }
	v_pk_mul_f32 v[52:53], v[52:53], v[190:191]
	v_mul_f32_e32 v54, v54, v172
	v_mul_f32_e32 v55, v55, v172
	v_mul_f32_e32 v56, v56, v172
	v_mul_f32_e32 v57, v57, v172
	v_mul_f32_e32 v50, v50, v172
	v_mul_f32_e32 v51, v51, v172
	v_mul_f32_e32 v52, v52, v172
	v_mul_f32_e32 v53, v53, v172
	v_cvt_pk_bf16_f32 v54, v54, v55
	v_cvt_pk_bf16_f32 v55, v56, v57
	v_cvt_pk_bf16_f32 v56, v50, v51
	v_cvt_pk_bf16_f32 v57, v52, v53
	v_add_u32_e32 v166, 0x10000, v164
	global_store_dwordx4 v166, v[54:57], s[4:5] offset:256
	v_permlane16_swap_b32_e32 v46, v42
	v_permlane16_swap_b32_e32 v47, v43
	v_permlane16_swap_b32_e32 v48, v44
	v_permlane16_swap_b32_e32 v49, v45
	v_cvt_f32_i32_e32 v46, v46
	v_cvt_f32_i32_e32 v47, v47
	v_cvt_f32_i32_e32 v48, v48
	v_cvt_f32_i32_e32 v49, v49
	v_cvt_f32_i32_e32 v42, v42
	v_cvt_f32_i32_e32 v43, v43
	v_cvt_f32_i32_e32 v44, v44
	v_cvt_f32_i32_e32 v45, v45
	v_pk_mul_f32 v[46:47], v[46:47], v[176:177]
	v_pk_mul_f32 v[48:49], v[48:49], v[178:179]
	v_pk_mul_f32 v[42:43], v[42:43], v[180:181]
	v_pk_mul_f32 v[44:45], v[44:45], v[182:183]
	v_mul_f32_e32 v46, v46, v173
	v_mul_f32_e32 v47, v47, v173
	v_mul_f32_e32 v48, v48, v173
	v_mul_f32_e32 v49, v49, v173
	v_mul_f32_e32 v42, v42, v173
	v_mul_f32_e32 v43, v43, v173
	v_mul_f32_e32 v44, v44, v173
	v_mul_f32_e32 v45, v45, v173
	v_cvt_pk_bf16_f32 v46, v46, v47
	v_cvt_pk_bf16_f32 v47, v48, v49
	v_cvt_pk_bf16_f32 v48, v42, v43
	v_cvt_pk_bf16_f32 v49, v44, v45
	v_add_u32_e32 v165, 0x12000, v164
	global_store_dwordx4 v165, v[46:49], s[4:5] offset:0
	v_permlane16_swap_b32_e32 v38, v34
	v_permlane16_swap_b32_e32 v39, v35
	v_permlane16_swap_b32_e32 v40, v36
	v_permlane16_swap_b32_e32 v41, v37
	v_cvt_f32_i32_e32 v38, v38
	v_cvt_f32_i32_e32 v39, v39
	v_cvt_f32_i32_e32 v40, v40
	v_cvt_f32_i32_e32 v41, v41
	v_cvt_f32_i32_e32 v34, v34
	v_cvt_f32_i32_e32 v35, v35
	v_cvt_f32_i32_e32 v36, v36
	v_cvt_f32_i32_e32 v37, v37
	v_pk_mul_f32 v[38:39], v[38:39], v[184:185]
	v_pk_mul_f32 v[40:41], v[40:41], v[186:187]
	v_pk_mul_f32 v[34:35], v[34:35], v[188:189]
	v_pk_mul_f32 v[36:37], v[36:37], v[190:191]
	v_mul_f32_e32 v38, v38, v173
	v_mul_f32_e32 v39, v39, v173
	v_mul_f32_e32 v40, v40, v173
	v_mul_f32_e32 v41, v41, v173
	v_mul_f32_e32 v34, v34, v173
	v_mul_f32_e32 v35, v35, v173
	v_mul_f32_e32 v36, v36, v173
	v_mul_f32_e32 v37, v37, v173
	v_cvt_pk_bf16_f32 v38, v38, v39
	v_cvt_pk_bf16_f32 v39, v40, v41
	v_cvt_pk_bf16_f32 v40, v34, v35
	v_cvt_pk_bf16_f32 v41, v36, v37
	v_add_u32_e32 v166, 0x12000, v164
	global_store_dwordx4 v166, v[38:41], s[4:5] offset:256
	v_permlane16_swap_b32_e32 v30, v26
	v_permlane16_swap_b32_e32 v31, v27
	v_permlane16_swap_b32_e32 v32, v28
	v_permlane16_swap_b32_e32 v33, v29
	v_cvt_f32_i32_e32 v30, v30
	v_cvt_f32_i32_e32 v31, v31
	v_cvt_f32_i32_e32 v32, v32
	v_cvt_f32_i32_e32 v33, v33
	v_cvt_f32_i32_e32 v26, v26
	v_cvt_f32_i32_e32 v27, v27
	v_cvt_f32_i32_e32 v28, v28
	v_cvt_f32_i32_e32 v29, v29
	v_pk_mul_f32 v[30:31], v[30:31], v[176:177]
	v_pk_mul_f32 v[32:33], v[32:33], v[178:179]
	v_pk_mul_f32 v[26:27], v[26:27], v[180:181]
	v_pk_mul_f32 v[28:29], v[28:29], v[182:183]
	v_mul_f32_e32 v30, v30, v174
	v_mul_f32_e32 v31, v31, v174
	v_mul_f32_e32 v32, v32, v174
	v_mul_f32_e32 v33, v33, v174
	v_mul_f32_e32 v26, v26, v174
	v_mul_f32_e32 v27, v27, v174
	v_mul_f32_e32 v28, v28, v174
	v_mul_f32_e32 v29, v29, v174
	v_cvt_pk_bf16_f32 v30, v30, v31
	v_cvt_pk_bf16_f32 v31, v32, v33
	v_cvt_pk_bf16_f32 v32, v26, v27
	v_cvt_pk_bf16_f32 v33, v28, v29
	v_add_u32_e32 v165, 0x14000, v164
	global_store_dwordx4 v165, v[30:33], s[4:5] offset:0
	v_permlane16_swap_b32_e32 v22, v18
	v_permlane16_swap_b32_e32 v23, v19
	v_permlane16_swap_b32_e32 v24, v20
	v_permlane16_swap_b32_e32 v25, v21
	v_cvt_f32_i32_e32 v22, v22
	v_cvt_f32_i32_e32 v23, v23
	v_cvt_f32_i32_e32 v24, v24
	v_cvt_f32_i32_e32 v25, v25
	v_cvt_f32_i32_e32 v18, v18
	v_cvt_f32_i32_e32 v19, v19
	v_cvt_f32_i32_e32 v20, v20
	v_cvt_f32_i32_e32 v21, v21
	v_pk_mul_f32 v[22:23], v[22:23], v[184:185]
	v_pk_mul_f32 v[24:25], v[24:25], v[186:187]
	v_pk_mul_f32 v[18:19], v[18:19], v[188:189]
	v_pk_mul_f32 v[20:21], v[20:21], v[190:191]
	v_mul_f32_e32 v22, v22, v174
	v_mul_f32_e32 v23, v23, v174
	v_mul_f32_e32 v24, v24, v174
	v_mul_f32_e32 v25, v25, v174
	v_mul_f32_e32 v18, v18, v174
	v_mul_f32_e32 v19, v19, v174
	v_mul_f32_e32 v20, v20, v174
	v_mul_f32_e32 v21, v21, v174
	v_cvt_pk_bf16_f32 v22, v22, v23
	v_cvt_pk_bf16_f32 v23, v24, v25
	v_cvt_pk_bf16_f32 v24, v18, v19
	v_cvt_pk_bf16_f32 v25, v20, v21
	v_add_u32_e32 v166, 0x14000, v164
	global_store_dwordx4 v166, v[22:25], s[4:5] offset:256
	v_permlane16_swap_b32_e32 v14, v10
	v_permlane16_swap_b32_e32 v15, v11
	v_permlane16_swap_b32_e32 v16, v12
	v_permlane16_swap_b32_e32 v17, v13
	v_cvt_f32_i32_e32 v14, v14
	v_cvt_f32_i32_e32 v15, v15
	v_cvt_f32_i32_e32 v16, v16
	v_cvt_f32_i32_e32 v17, v17
	v_cvt_f32_i32_e32 v10, v10
	v_cvt_f32_i32_e32 v11, v11
	v_cvt_f32_i32_e32 v12, v12
	v_cvt_f32_i32_e32 v13, v13
	v_pk_mul_f32 v[14:15], v[14:15], v[176:177]
	v_pk_mul_f32 v[16:17], v[16:17], v[178:179]
	v_pk_mul_f32 v[10:11], v[10:11], v[180:181]
	v_pk_mul_f32 v[12:13], v[12:13], v[182:183]
	v_mul_f32_e32 v14, v14, v175
	v_mul_f32_e32 v15, v15, v175
	v_mul_f32_e32 v16, v16, v175
	v_mul_f32_e32 v17, v17, v175
	v_mul_f32_e32 v10, v10, v175
	v_mul_f32_e32 v11, v11, v175
	v_mul_f32_e32 v12, v12, v175
	v_mul_f32_e32 v13, v13, v175
	v_cvt_pk_bf16_f32 v14, v14, v15
	v_cvt_pk_bf16_f32 v15, v16, v17
	v_cvt_pk_bf16_f32 v16, v10, v11
	v_cvt_pk_bf16_f32 v17, v12, v13
	v_add_u32_e32 v165, 0x16000, v164
	global_store_dwordx4 v165, v[14:17], s[4:5] offset:0
	v_permlane16_swap_b32_e32 v6, v2
	v_permlane16_swap_b32_e32 v7, v3
	v_permlane16_swap_b32_e32 v8, v4
	v_permlane16_swap_b32_e32 v9, v5
	v_cvt_f32_i32_e32 v6, v6
	v_cvt_f32_i32_e32 v7, v7
	v_cvt_f32_i32_e32 v8, v8
	v_cvt_f32_i32_e32 v9, v9
	v_cvt_f32_i32_e32 v2, v2
	v_cvt_f32_i32_e32 v3, v3
	v_cvt_f32_i32_e32 v4, v4
	v_cvt_f32_i32_e32 v5, v5
	v_pk_mul_f32 v[6:7], v[6:7], v[184:185]
	v_pk_mul_f32 v[8:9], v[8:9], v[186:187]
	v_pk_mul_f32 v[2:3], v[2:3], v[188:189]
	v_pk_mul_f32 v[4:5], v[4:5], v[190:191]
	v_mul_f32_e32 v6, v6, v175
	v_mul_f32_e32 v7, v7, v175
	v_mul_f32_e32 v8, v8, v175
	v_mul_f32_e32 v9, v9, v175
	v_mul_f32_e32 v2, v2, v175
	v_mul_f32_e32 v3, v3, v175
	v_mul_f32_e32 v4, v4, v175
	v_mul_f32_e32 v5, v5, v175
	v_cvt_pk_bf16_f32 v6, v6, v7
	v_cvt_pk_bf16_f32 v7, v8, v9
	v_cvt_pk_bf16_f32 v8, v2, v3
	v_cvt_pk_bf16_f32 v9, v4, v5
	v_add_u32_e32 v166, 0x16000, v164
	global_store_dwordx4 v166, v[6:9], s[4:5] offset:256
	s_waitcnt vmcnt(0)
	s_barrier

; __device__ __forceinline__ unsigned cvt_pk_bf16(float lo, float hi) { unsigned r; asm("v_cvt_pk_bf16_f32 %0, %1, %2" : "=v"(r) : "v"(lo), "v"(hi)); return r; }
; __device__ __forceinline__ f32x4 ld_bf4(const bf16_t* p) { const u32x2 w = *(const u32x2*)p; return (f32x4){bf_lo(w.x), bf_hi(w.x), bf_lo(w.y), bf_hi(w.y)}; }
;     __device__ __forceinline__ void operator()(const f32x4 (&acc)[2][2][4][2], const pg8::Unit& u, int wr, int wc, int fr, int fq) const {
;         const int row0 = u.pm * 256 + wr * 64 + fr, col0 = u.pn * 256 + wc * 32 + 4 * fq;
;         f32x4 swv[2][2];
; #pragma unroll
;         for (int bj = 0; bj < 2; ++bj)
; #pragma unroll
;             for (int n = 0; n < 2; ++n) swv[bj][n] = *(const f32x4*)(sw + col0 + bj * 128 + n * 16);
;         float sav[2][4];
; #pragma unroll
;         for (int ai = 0; ai < 2; ++ai)
; #pragma unroll
;             for (int m = 0; m < 4; ++m) sav[ai][m] = sa[row0 + ai * 128 + m * 16];
; #pragma unroll
;         for (int am = 0; am < 4; ++am) { const int ai = am >> 1, m0 = 2 * (am & 1); f32x4 r[2][2][2];
; #pragma unroll
;             for (int mm = 0; mm < 2; ++mm) { const size_t off = (size_t)(row0 + ai * 128 + (m0 + mm) * 16) * DM + col0;
; #pragma unroll
;                 for (int bj = 0; bj < 2; ++bj)
; #pragma unroll
;                     for (int n = 0; n < 2; ++n) r[mm][bj][n] = ld_bf4(X1 + off + bj * 128 + n * 16); }
; #pragma unroll
;             for (int mm = 0; mm < 2; ++mm) { const size_t off = (size_t)(row0 + ai * 128 + (m0 + mm) * 16) * DM + col0;
; #pragma unroll
;                 for (int bj = 0; bj < 2; ++bj)
; #pragma unroll
;                     for (int n = 0; n < 2; ++n) { const i32x4 q = __builtin_bit_cast(i32x4, acc[ai][bj][m0 + mm][n]);
;                         const f32x4 v = (f32x4){(float)q[0], (float)q[1], (float)q[2], (float)q[3]} * swv[bj][n] * sav[ai][m0 + mm] + r[mm][bj][n];
;                         u32x2 w; w.x = cvt_pk_bf16(v[0], v[1]); w.y = cvt_pk_bf16(v[2], v[3]); *(u32x2*)(X2 + off + bj * 128 + n * 16) = w; } } }
;     }
.LBB0_2875:
	v_lshl_add_u32 v182, s58, 8, v173
	v_and_b32_e32 v183, 1, v235
	v_mul_u32_u24_e32 v183, 12, v183
	v_add_u32_e32 v183, v183, v179
	v_lshl_or_b32 v183, s59, 8, v183
	v_lshlrev_b32_e32 v153, 2, v183
	v_lshlrev_b32_e32 v154, 13, v182
	v_lshl_add_u32 v154, v183, 1, v154
	v_mbcnt_lo_u32_b32 v152, -1, 0
	v_mbcnt_hi_u32_b32 v152, -1, v152
	v_and_b32_e32 v158, 64, v173
	v_add_u32_e32 v152, v152, v158
	v_lshl_add_u32 v152, s58, 8, v152
	v_lshlrev_b32_e32 v152, 2, v152
	v_and_b32_e32 v158, 15, v173
	v_lshlrev_b32_e32 v158, 2, v158
	global_load_dword v204, v152, s[8:9]
	global_load_dword v205, v152, s[8:9] offset:512
	global_load_dwordx4 v[184:187], v153, s[10:11] offset:0
	global_load_dwordx4 v[188:191], v153, s[10:11] offset:16
	global_load_dwordx4 v[192:195], v153, s[10:11] offset:512
	global_load_dwordx4 v[196:199], v153, s[10:11] offset:528
	v_mov_b32_e32 v156, v154
	global_load_dwordx4 v[200:203], v156, s[16:17] offset:0
	v_mov_b32_e32 v157, v154
	global_load_dwordx4 v[208:211], v157, s[16:17] offset:256
	v_add_u32_e32 v156, 0x20000, v154
	global_load_dwordx4 v[212:215], v156, s[16:17] offset:0
	v_add_u32_e32 v157, 0x20000, v154
	global_load_dwordx4 v[216:219], v157, s[16:17] offset:256
	v_add_u32_e32 v156, 0x40000, v154
	global_load_dwordx4 v[220:223], v156, s[16:17] offset:0
	v_add_u32_e32 v157, 0x40000, v154
	global_load_dwordx4 v[224:227], v157, s[16:17] offset:256
	v_add_u32_e32 v156, 0x60000, v154
	global_load_dwordx4 v[228:231], v156, s[16:17] offset:0
	v_add_u32_e32 v157, 0x60000, v154
	global_load_dwordx4 v[98:101], v157, s[16:17] offset:256
	v_permlane16_swap_b32_e32 v94, v138
	v_permlane16_swap_b32_e32 v95, v139
	v_permlane16_swap_b32_e32 v96, v140
	v_permlane16_swap_b32_e32 v97, v141
	v_cvt_f32_i32_e32 v94, v94
	v_cvt_f32_i32_e32 v95, v95
	v_cvt_f32_i32_e32 v96, v96
	v_cvt_f32_i32_e32 v97, v97
	v_cvt_f32_i32_e32 v138, v138
	v_cvt_f32_i32_e32 v139, v139
	v_cvt_f32_i32_e32 v140, v140
	v_cvt_f32_i32_e32 v141, v141
	s_waitcnt vmcnt(7)
	ds_bpermute_b32 v160, v158, v204
	ds_bpermute_b32 v161, v158, v204 offset:64
	ds_bpermute_b32 v162, v158, v204 offset:128
	ds_bpermute_b32 v163, v158, v204 offset:192
	ds_bpermute_b32 v164, v158, v205
	ds_bpermute_b32 v166, v158, v205 offset:64
	ds_bpermute_b32 v167, v158, v205 offset:128
	ds_bpermute_b32 v168, v158, v205 offset:192
	s_waitcnt lgkmcnt(0)
	v_pk_mul_f32 v[94:95], v[94:95], v[184:185]
	v_pk_mul_f32 v[96:97], v[96:97], v[186:187]
	v_pk_mul_f32 v[138:139], v[138:139], v[188:189]
	v_pk_mul_f32 v[140:141], v[140:141], v[190:191]
	v_lshlrev_b32_e32 v102, 16, v200
	v_and_b32_e32 v200, 0xffff0000, v200
	v_lshlrev_b32_e32 v103, 16, v201
	v_and_b32_e32 v201, 0xffff0000, v201
	v_lshlrev_b32_e32 v104, 16, v202
	v_and_b32_e32 v202, 0xffff0000, v202
	v_lshlrev_b32_e32 v105, 16, v203
	v_and_b32_e32 v203, 0xffff0000, v203
	v_fma_f32 v94, v94, v160, v102
	v_fma_f32 v95, v95, v160, v200
	v_fma_f32 v96, v96, v160, v103
	v_fma_f32 v97, v97, v160, v201
	v_fma_f32 v138, v138, v160, v104
	v_fma_f32 v139, v139, v160, v202
	v_fma_f32 v140, v140, v160, v105
	v_fma_f32 v141, v141, v160, v203
	v_cvt_pk_bf16_f32 v94, v94, v95
	v_cvt_pk_bf16_f32 v95, v96, v97
	v_cvt_pk_bf16_f32 v96, v138, v139
	v_cvt_pk_bf16_f32 v97, v140, v141
	v_permlane16_swap_b32_e32 v134, v126
	v_permlane16_swap_b32_e32 v135, v127
	v_permlane16_swap_b32_e32 v136, v128
	v_permlane16_swap_b32_e32 v137, v129
	v_cvt_f32_i32_e32 v134, v134
	v_cvt_f32_i32_e32 v135, v135
	v_cvt_f32_i32_e32 v136, v136
	v_cvt_f32_i32_e32 v137, v137
	v_cvt_f32_i32_e32 v126, v126
	v_cvt_f32_i32_e32 v127, v127
	v_cvt_f32_i32_e32 v128, v128
	v_cvt_f32_i32_e32 v129, v129
	s_waitcnt vmcnt(6)
	v_pk_mul_f32 v[134:135], v[134:135], v[192:193]
	v_pk_mul_f32 v[136:137], v[136:137], v[194:195]
	v_pk_mul_f32 v[126:127], v[126:127], v[196:197]
	v_pk_mul_f32 v[128:129], v[128:129], v[198:199]
	v_lshlrev_b32_e32 v102, 16, v208
	v_and_b32_e32 v208, 0xffff0000, v208
	v_lshlrev_b32_e32 v103, 16, v209
	v_and_b32_e32 v209, 0xffff0000, v209
	v_lshlrev_b32_e32 v104, 16, v210
	v_and_b32_e32 v210, 0xffff0000, v210
	v_lshlrev_b32_e32 v105, 16, v211
	v_and_b32_e32 v211, 0xffff0000, v211
	v_fma_f32 v134, v134, v160, v102
	v_fma_f32 v135, v135, v160, v208
	v_fma_f32 v136, v136, v160, v103
	v_fma_f32 v137, v137, v160, v209
	v_fma_f32 v126, v126, v160, v104
	v_fma_f32 v127, v127, v160, v210
	v_fma_f32 v128, v128, v160, v105
	v_fma_f32 v129, v129, v160, v211
	v_cvt_pk_bf16_f32 v134, v134, v135
	v_cvt_pk_bf16_f32 v135, v136, v137
	v_cvt_pk_bf16_f32 v136, v126, v127
	v_cvt_pk_bf16_f32 v137, v128, v129
	v_permlane16_swap_b32_e32 v130, v122
	v_permlane16_swap_b32_e32 v131, v123
	v_permlane16_swap_b32_e32 v132, v124
	v_permlane16_swap_b32_e32 v133, v125
	v_cvt_f32_i32_e32 v130, v130
	v_cvt_f32_i32_e32 v131, v131
	v_cvt_f32_i32_e32 v132, v132
	v_cvt_f32_i32_e32 v133, v133
	v_cvt_f32_i32_e32 v122, v122
	v_cvt_f32_i32_e32 v123, v123
	v_cvt_f32_i32_e32 v124, v124
	v_cvt_f32_i32_e32 v125, v125
	s_waitcnt vmcnt(5)
	v_pk_mul_f32 v[130:131], v[130:131], v[184:185]
	v_pk_mul_f32 v[132:133], v[132:133], v[186:187]
	v_pk_mul_f32 v[122:123], v[122:123], v[188:189]
	v_pk_mul_f32 v[124:125], v[124:125], v[190:191]
	v_lshlrev_b32_e32 v102, 16, v212
	v_and_b32_e32 v212, 0xffff0000, v212
	v_lshlrev_b32_e32 v103, 16, v213
	v_and_b32_e32 v213, 0xffff0000, v213
	v_lshlrev_b32_e32 v104, 16, v214
	v_and_b32_e32 v214, 0xffff0000, v214
	v_lshlrev_b32_e32 v105, 16, v215
	v_and_b32_e32 v215, 0xffff0000, v215
	v_fma_f32 v130, v130, v161, v102
	v_fma_f32 v131, v131, v161, v212
	v_fma_f32 v132, v132, v161, v103
	v_fma_f32 v133, v133, v161, v213
	v_fma_f32 v122, v122, v161, v104
	v_fma_f32 v123, v123, v161, v214
	v_fma_f32 v124, v124, v161, v105
	v_fma_f32 v125, v125, v161, v215
	v_cvt_pk_bf16_f32 v130, v130, v131
	v_cvt_pk_bf16_f32 v131, v132, v133
	v_cvt_pk_bf16_f32 v132, v122, v123
	v_cvt_pk_bf16_f32 v133, v124, v125
	v_permlane16_swap_b32_e32 v118, v114
	v_permlane16_swap_b32_e32 v119, v115
	v_permlane16_swap_b32_e32 v120, v116
	v_permlane16_swap_b32_e32 v121, v117
	v_cvt_f32_i32_e32 v118, v118
	v_cvt_f32_i32_e32 v119, v119
	v_cvt_f32_i32_e32 v120, v120
	v_cvt_f32_i32_e32 v121, v121
	v_cvt_f32_i32_e32 v114, v114
	v_cvt_f32_i32_e32 v115, v115
	v_cvt_f32_i32_e32 v116, v116
	v_cvt_f32_i32_e32 v117, v117
	s_waitcnt vmcnt(4)
; __device__ __forceinline__ unsigned cvt_pk_bf16(float lo, float hi) { unsigned r; asm("v_cvt_pk_bf16_f32 %0, %1, %2" : "=v"(r) : "v"(lo), "v"(hi)); return r; }
;     __device__ __forceinline__ void operator()(const f32x4 (&acc)[2][2][4][2], const pg8::Unit& u, int wr, int wc, int fr, int fq) const {
;     ...
;             for (int mm = 0; mm < 2; ++mm) { const size_t off = (size_t)(row0 + ai * 128 + (m0 + mm) * 16) * DM + col0;
; #pragma unroll
;                 for (int bj = 0; bj < 2; ++bj)
; #pragma unroll
;                     for (int n = 0; n < 2; ++n) { const i32x4 q = __builtin_bit_cast(i32x4, acc[ai][bj][m0 + mm][n]);
;                         const f32x4 v = (f32x4){(float)q[0], (float)q[1], (float)q[2], (float)q[3]} * swv[bj][n] * sav[ai][m0 + mm] + r[mm][bj][n];
;                         u32x2 w; w.x = cvt_pk_bf16(v[0], v[1]); w.y = cvt_pk_bf16(v[2], v[3]); *(u32x2*)(X2 + off + bj * 128 + n * 16) = w; } } }
	v_pk_mul_f32 v[118:119], v[118:119], v[192:193]
	v_pk_mul_f32 v[120:121], v[120:121], v[194:195]
	v_pk_mul_f32 v[114:115], v[114:115], v[196:197]
	v_pk_mul_f32 v[116:117], v[116:117], v[198:199]
	v_lshlrev_b32_e32 v102, 16, v216
	v_and_b32_e32 v216, 0xffff0000, v216
	v_lshlrev_b32_e32 v103, 16, v217
	v_and_b32_e32 v217, 0xffff0000, v217
	v_lshlrev_b32_e32 v104, 16, v218
	v_and_b32_e32 v218, 0xffff0000, v218
	v_lshlrev_b32_e32 v105, 16, v219
	v_and_b32_e32 v219, 0xffff0000, v219
	v_fma_f32 v118, v118, v161, v102
	v_fma_f32 v119, v119, v161, v216
	v_fma_f32 v120, v120, v161, v103
	v_fma_f32 v121, v121, v161, v217
	v_fma_f32 v114, v114, v161, v104
	v_fma_f32 v115, v115, v161, v218
	v_fma_f32 v116, v116, v161, v105
	v_fma_f32 v117, v117, v161, v219
	v_cvt_pk_bf16_f32 v118, v118, v119
	v_cvt_pk_bf16_f32 v119, v120, v121
	v_cvt_pk_bf16_f32 v120, v114, v115
	v_cvt_pk_bf16_f32 v121, v116, v117
	v_permlane16_swap_b32_e32 v110, v106
	v_permlane16_swap_b32_e32 v111, v107
	v_permlane16_swap_b32_e32 v112, v108
	v_permlane16_swap_b32_e32 v113, v109
	v_cvt_f32_i32_e32 v110, v110
	v_cvt_f32_i32_e32 v111, v111
	v_cvt_f32_i32_e32 v112, v112
	v_cvt_f32_i32_e32 v113, v113
	v_cvt_f32_i32_e32 v106, v106
	v_cvt_f32_i32_e32 v107, v107
	v_cvt_f32_i32_e32 v108, v108
	v_cvt_f32_i32_e32 v109, v109
	s_waitcnt vmcnt(3)
	v_pk_mul_f32 v[110:111], v[110:111], v[184:185]
	v_pk_mul_f32 v[112:113], v[112:113], v[186:187]
	v_pk_mul_f32 v[106:107], v[106:107], v[188:189]
	v_pk_mul_f32 v[108:109], v[108:109], v[190:191]
	v_lshlrev_b32_e32 v102, 16, v220
	v_and_b32_e32 v220, 0xffff0000, v220
	v_lshlrev_b32_e32 v103, 16, v221
	v_and_b32_e32 v221, 0xffff0000, v221
	v_lshlrev_b32_e32 v104, 16, v222
	v_and_b32_e32 v222, 0xffff0000, v222
	v_lshlrev_b32_e32 v105, 16, v223
	v_and_b32_e32 v223, 0xffff0000, v223
	v_fma_f32 v110, v110, v162, v102
	v_fma_f32 v111, v111, v162, v220
	v_fma_f32 v112, v112, v162, v103
	v_fma_f32 v113, v113, v162, v221
	v_fma_f32 v106, v106, v162, v104
	v_fma_f32 v107, v107, v162, v222
	v_fma_f32 v108, v108, v162, v105
	v_fma_f32 v109, v109, v162, v223
	v_cvt_pk_bf16_f32 v110, v110, v111
	v_cvt_pk_bf16_f32 v111, v112, v113
	v_cvt_pk_bf16_f32 v112, v106, v107
	v_cvt_pk_bf16_f32 v113, v108, v109
	v_permlane16_swap_b32_e32 v86, v78
	v_permlane16_swap_b32_e32 v87, v79
	v_permlane16_swap_b32_e32 v88, v80
	v_permlane16_swap_b32_e32 v89, v81
	v_cvt_f32_i32_e32 v86, v86
	v_cvt_f32_i32_e32 v87, v87
	v_cvt_f32_i32_e32 v88, v88
	v_cvt_f32_i32_e32 v89, v89
	v_cvt_f32_i32_e32 v78, v78
	v_cvt_f32_i32_e32 v79, v79
	v_cvt_f32_i32_e32 v80, v80
	v_cvt_f32_i32_e32 v81, v81
	s_waitcnt vmcnt(2)
	v_pk_mul_f32 v[86:87], v[86:87], v[192:193]
	v_pk_mul_f32 v[88:89], v[88:89], v[194:195]
	v_pk_mul_f32 v[78:79], v[78:79], v[196:197]
	v_pk_mul_f32 v[80:81], v[80:81], v[198:199]
	v_lshlrev_b32_e32 v102, 16, v224
	v_and_b32_e32 v224, 0xffff0000, v224
	v_lshlrev_b32_e32 v103, 16, v225
	v_and_b32_e32 v225, 0xffff0000, v225
	v_lshlrev_b32_e32 v104, 16, v226
	v_and_b32_e32 v226, 0xffff0000, v226
	v_lshlrev_b32_e32 v105, 16, v227
	v_and_b32_e32 v227, 0xffff0000, v227
	v_fma_f32 v86, v86, v162, v102
	v_fma_f32 v87, v87, v162, v224
	v_fma_f32 v88, v88, v162, v103
	v_fma_f32 v89, v89, v162, v225
	v_fma_f32 v78, v78, v162, v104
	v_fma_f32 v79, v79, v162, v226
	v_fma_f32 v80, v80, v162, v105
	v_fma_f32 v81, v81, v162, v227
	v_cvt_pk_bf16_f32 v86, v86, v87
	v_cvt_pk_bf16_f32 v87, v88, v89
	v_cvt_pk_bf16_f32 v88, v78, v79
	v_cvt_pk_bf16_f32 v89, v80, v81
	v_permlane16_swap_b32_e32 v82, v74
	v_permlane16_swap_b32_e32 v83, v75
	v_permlane16_swap_b32_e32 v84, v76
	v_permlane16_swap_b32_e32 v85, v77
	v_cvt_f32_i32_e32 v82, v82
	v_cvt_f32_i32_e32 v83, v83
	v_cvt_f32_i32_e32 v84, v84
	v_cvt_f32_i32_e32 v85, v85
	v_cvt_f32_i32_e32 v74, v74
	v_cvt_f32_i32_e32 v75, v75
	v_cvt_f32_i32_e32 v76, v76
	v_cvt_f32_i32_e32 v77, v77
	s_waitcnt vmcnt(1)
	v_pk_mul_f32 v[82:83], v[82:83], v[184:185]
	v_pk_mul_f32 v[84:85], v[84:85], v[186:187]
	v_pk_mul_f32 v[74:75], v[74:75], v[188:189]
	v_pk_mul_f32 v[76:77], v[76:77], v[190:191]
	v_lshlrev_b32_e32 v102, 16, v228
	v_and_b32_e32 v228, 0xffff0000, v228
	v_lshlrev_b32_e32 v103, 16, v229
	v_and_b32_e32 v229, 0xffff0000, v229
	v_lshlrev_b32_e32 v104, 16, v230
	v_and_b32_e32 v230, 0xffff0000, v230
	v_lshlrev_b32_e32 v105, 16, v231
	v_and_b32_e32 v231, 0xffff0000, v231
	v_fma_f32 v82, v82, v163, v102
	v_fma_f32 v83, v83, v163, v228
	v_fma_f32 v84, v84, v163, v103
	v_fma_f32 v85, v85, v163, v229
	v_fma_f32 v74, v74, v163, v104
	v_fma_f32 v75, v75, v163, v230
	v_fma_f32 v76, v76, v163, v105
	v_fma_f32 v77, v77, v163, v231
	v_cvt_pk_bf16_f32 v82, v82, v83
	v_cvt_pk_bf16_f32 v83, v84, v85
	v_cvt_pk_bf16_f32 v84, v74, v75
	v_cvt_pk_bf16_f32 v85, v76, v77
	v_permlane16_swap_b32_e32 v70, v66
	v_permlane16_swap_b32_e32 v71, v67
	v_permlane16_swap_b32_e32 v72, v68
	v_permlane16_swap_b32_e32 v73, v69
	v_cvt_f32_i32_e32 v70, v70
	v_cvt_f32_i32_e32 v71, v71
	v_cvt_f32_i32_e32 v72, v72
	v_cvt_f32_i32_e32 v73, v73
	v_cvt_f32_i32_e32 v66, v66
	v_cvt_f32_i32_e32 v67, v67
	v_cvt_f32_i32_e32 v68, v68
	v_cvt_f32_i32_e32 v69, v69
	s_waitcnt vmcnt(0)
; __device__ __forceinline__ unsigned cvt_pk_bf16(float lo, float hi) { unsigned r; asm("v_cvt_pk_bf16_f32 %0, %1, %2" : "=v"(r) : "v"(lo), "v"(hi)); return r; }
; __device__ __forceinline__ f32x4 ld_bf4(const bf16_t* p) { const u32x2 w = *(const u32x2*)p; return (f32x4){bf_lo(w.x), bf_hi(w.x), bf_lo(w.y), bf_hi(w.y)}; }
;     __device__ __forceinline__ void operator()(const f32x4 (&acc)[2][2][4][2], const pg8::Unit& u, int wr, int wc, int fr, int fq) const {
;     ...
;             for (int mm = 0; mm < 2; ++mm) { const size_t off = (size_t)(row0 + ai * 128 + (m0 + mm) * 16) * DM + col0;
; #pragma unroll
;                 for (int bj = 0; bj < 2; ++bj)
; #pragma unroll
;                     for (int n = 0; n < 2; ++n) r[mm][bj][n] = ld_bf4(X1 + off + bj * 128 + n * 16); }
; #pragma unroll
;             for (int mm = 0; mm < 2; ++mm) { const size_t off = (size_t)(row0 + ai * 128 + (m0 + mm) * 16) * DM + col0;
; #pragma unroll
;                 for (int bj = 0; bj < 2; ++bj)
; #pragma unroll
;                     for (int n = 0; n < 2; ++n) { const i32x4 q = __builtin_bit_cast(i32x4, acc[ai][bj][m0 + mm][n]);
;                         const f32x4 v = (f32x4){(float)q[0], (float)q[1], (float)q[2], (float)q[3]} * swv[bj][n] * sav[ai][m0 + mm] + r[mm][bj][n];
;                         u32x2 w; w.x = cvt_pk_bf16(v[0], v[1]); w.y = cvt_pk_bf16(v[2], v[3]); *(u32x2*)(X2 + off + bj * 128 + n * 16) = w; } } }
	v_pk_mul_f32 v[70:71], v[70:71], v[192:193]
	v_pk_mul_f32 v[72:73], v[72:73], v[194:195]
	v_pk_mul_f32 v[66:67], v[66:67], v[196:197]
	v_pk_mul_f32 v[68:69], v[68:69], v[198:199]
	v_lshlrev_b32_e32 v102, 16, v98
	v_and_b32_e32 v98, 0xffff0000, v98
	v_lshlrev_b32_e32 v103, 16, v99
	v_and_b32_e32 v99, 0xffff0000, v99
	v_lshlrev_b32_e32 v104, 16, v100
	v_and_b32_e32 v100, 0xffff0000, v100
	v_lshlrev_b32_e32 v105, 16, v101
	v_and_b32_e32 v101, 0xffff0000, v101
	v_fma_f32 v70, v70, v163, v102
	v_fma_f32 v71, v71, v163, v98
	v_fma_f32 v72, v72, v163, v103
	v_fma_f32 v73, v73, v163, v99
	v_fma_f32 v66, v66, v163, v104
	v_fma_f32 v67, v67, v163, v100
	v_fma_f32 v68, v68, v163, v105
	v_fma_f32 v69, v69, v163, v101
	v_cvt_pk_bf16_f32 v70, v70, v71
	v_cvt_pk_bf16_f32 v71, v72, v73
	v_cvt_pk_bf16_f32 v72, v66, v67
	v_cvt_pk_bf16_f32 v73, v68, v69
	v_add_u32_e32 v156, 0x100000, v154
	global_load_dwordx4 v[138:141], v156, s[16:17] offset:0
	v_add_u32_e32 v157, 0x100000, v154
	global_load_dwordx4 v[126:129], v157, s[16:17] offset:256
	v_add_u32_e32 v156, 0x120000, v154
	global_load_dwordx4 v[122:125], v156, s[16:17] offset:0
	v_add_u32_e32 v157, 0x120000, v154
	global_load_dwordx4 v[114:117], v157, s[16:17] offset:256
	v_add_u32_e32 v156, 0x140000, v154
	global_load_dwordx4 v[106:109], v156, s[16:17] offset:0
	v_add_u32_e32 v157, 0x140000, v154
	global_load_dwordx4 v[78:81], v157, s[16:17] offset:256
	v_add_u32_e32 v156, 0x160000, v154
	global_load_dwordx4 v[74:77], v156, s[16:17] offset:0
	v_add_u32_e32 v157, 0x160000, v154
	global_load_dwordx4 v[66:69], v157, s[16:17] offset:256
	v_mov_b32_e32 v156, v154
	global_store_dwordx4 v156, v[94:97], s[18:19] offset:0
	v_mov_b32_e32 v157, v154
	global_store_dwordx4 v157, v[134:137], s[18:19] offset:256
	v_add_u32_e32 v156, 0x20000, v154
	global_store_dwordx4 v156, v[130:133], s[18:19] offset:0
	v_add_u32_e32 v157, 0x20000, v154
	global_store_dwordx4 v157, v[118:121], s[18:19] offset:256
	v_add_u32_e32 v156, 0x40000, v154
	global_store_dwordx4 v156, v[110:113], s[18:19] offset:0
	v_add_u32_e32 v157, 0x40000, v154
	global_store_dwordx4 v157, v[86:89], s[18:19] offset:256
	v_add_u32_e32 v156, 0x60000, v154
	global_store_dwordx4 v156, v[82:85], s[18:19] offset:0
	v_add_u32_e32 v157, 0x60000, v154
	global_store_dwordx4 v157, v[70:73], s[18:19] offset:256
	v_permlane16_swap_b32_e32 v62, v58
	v_permlane16_swap_b32_e32 v63, v59
	v_permlane16_swap_b32_e32 v64, v60
	v_permlane16_swap_b32_e32 v65, v61
	v_cvt_f32_i32_e32 v62, v62
	v_cvt_f32_i32_e32 v63, v63
	v_cvt_f32_i32_e32 v64, v64
	v_cvt_f32_i32_e32 v65, v65
	v_cvt_f32_i32_e32 v58, v58
	v_cvt_f32_i32_e32 v59, v59
	v_cvt_f32_i32_e32 v60, v60
	v_cvt_f32_i32_e32 v61, v61
	s_waitcnt vmcnt(15)
	v_pk_mul_f32 v[62:63], v[62:63], v[184:185]
	v_pk_mul_f32 v[64:65], v[64:65], v[186:187]
	v_pk_mul_f32 v[58:59], v[58:59], v[188:189]
	v_pk_mul_f32 v[60:61], v[60:61], v[190:191]
	v_lshlrev_b32_e32 v102, 16, v138
	v_and_b32_e32 v138, 0xffff0000, v138
	v_lshlrev_b32_e32 v103, 16, v139
	v_and_b32_e32 v139, 0xffff0000, v139
	v_lshlrev_b32_e32 v104, 16, v140
	v_and_b32_e32 v140, 0xffff0000, v140
	v_lshlrev_b32_e32 v105, 16, v141
	v_and_b32_e32 v141, 0xffff0000, v141
	v_fma_f32 v62, v62, v164, v102
	v_fma_f32 v63, v63, v164, v138
	v_fma_f32 v64, v64, v164, v103
	v_fma_f32 v65, v65, v164, v139
	v_fma_f32 v58, v58, v164, v104
	v_fma_f32 v59, v59, v164, v140
	v_fma_f32 v60, v60, v164, v105
	v_fma_f32 v61, v61, v164, v141
	v_cvt_pk_bf16_f32 v62, v62, v63
	v_cvt_pk_bf16_f32 v63, v64, v65
	v_cvt_pk_bf16_f32 v64, v58, v59
	v_cvt_pk_bf16_f32 v65, v60, v61
	v_add_u32_e32 v156, 0x100000, v154
	global_store_dwordx4 v156, v[62:65], s[18:19] offset:0
	v_permlane16_swap_b32_e32 v54, v46
	v_permlane16_swap_b32_e32 v55, v47
	v_permlane16_swap_b32_e32 v56, v48
	v_permlane16_swap_b32_e32 v57, v49
	v_cvt_f32_i32_e32 v54, v54
	v_cvt_f32_i32_e32 v55, v55
	v_cvt_f32_i32_e32 v56, v56
	v_cvt_f32_i32_e32 v57, v57
	v_cvt_f32_i32_e32 v46, v46
	v_cvt_f32_i32_e32 v47, v47
	v_cvt_f32_i32_e32 v48, v48
	v_cvt_f32_i32_e32 v49, v49
	s_waitcnt vmcnt(15)
	v_pk_mul_f32 v[54:55], v[54:55], v[192:193]
	v_pk_mul_f32 v[56:57], v[56:57], v[194:195]
	v_pk_mul_f32 v[46:47], v[46:47], v[196:197]
	v_pk_mul_f32 v[48:49], v[48:49], v[198:199]
	v_lshlrev_b32_e32 v102, 16, v126
	v_and_b32_e32 v126, 0xffff0000, v126
	v_lshlrev_b32_e32 v103, 16, v127
	v_and_b32_e32 v127, 0xffff0000, v127
	v_lshlrev_b32_e32 v104, 16, v128
	v_and_b32_e32 v128, 0xffff0000, v128
	v_lshlrev_b32_e32 v105, 16, v129
	v_and_b32_e32 v129, 0xffff0000, v129
	v_fma_f32 v54, v54, v164, v102
	v_fma_f32 v55, v55, v164, v126
	v_fma_f32 v56, v56, v164, v103
	v_fma_f32 v57, v57, v164, v127
	v_fma_f32 v46, v46, v164, v104
	v_fma_f32 v47, v47, v164, v128
	v_fma_f32 v48, v48, v164, v105
	v_fma_f32 v49, v49, v164, v129
	v_cvt_pk_bf16_f32 v54, v54, v55
	v_cvt_pk_bf16_f32 v55, v56, v57
	v_cvt_pk_bf16_f32 v56, v46, v47
	v_cvt_pk_bf16_f32 v57, v48, v49
	v_add_u32_e32 v157, 0x100000, v154
	global_store_dwordx4 v157, v[54:57], s[18:19] offset:256
	v_permlane16_swap_b32_e32 v50, v42
	v_permlane16_swap_b32_e32 v51, v43
	v_permlane16_swap_b32_e32 v52, v44
	v_permlane16_swap_b32_e32 v53, v45
	v_cvt_f32_i32_e32 v50, v50
	v_cvt_f32_i32_e32 v51, v51
	v_cvt_f32_i32_e32 v52, v52
	v_cvt_f32_i32_e32 v53, v53
	v_cvt_f32_i32_e32 v42, v42
	v_cvt_f32_i32_e32 v43, v43
	v_cvt_f32_i32_e32 v44, v44
	v_cvt_f32_i32_e32 v45, v45
	s_waitcnt vmcnt(15)
; __device__ __forceinline__ unsigned cvt_pk_bf16(float lo, float hi) { unsigned r; asm("v_cvt_pk_bf16_f32 %0, %1, %2" : "=v"(r) : "v"(lo), "v"(hi)); return r; }
;     __device__ __forceinline__ void operator()(const f32x4 (&acc)[2][2][4][2], const pg8::Unit& u, int wr, int wc, int fr, int fq) const {
;     ...
;             for (int mm = 0; mm < 2; ++mm) { const size_t off = (size_t)(row0 + ai * 128 + (m0 + mm) * 16) * DM + col0;
; #pragma unroll
;                 for (int bj = 0; bj < 2; ++bj)
; #pragma unroll
;                     for (int n = 0; n < 2; ++n) { const i32x4 q = __builtin_bit_cast(i32x4, acc[ai][bj][m0 + mm][n]);
;                         const f32x4 v = (f32x4){(float)q[0], (float)q[1], (float)q[2], (float)q[3]} * swv[bj][n] * sav[ai][m0 + mm] + r[mm][bj][n];
;                         u32x2 w; w.x = cvt_pk_bf16(v[0], v[1]); w.y = cvt_pk_bf16(v[2], v[3]); *(u32x2*)(X2 + off + bj * 128 + n * 16) = w; } } }
	v_pk_mul_f32 v[50:51], v[50:51], v[184:185]
	v_pk_mul_f32 v[52:53], v[52:53], v[186:187]
	v_pk_mul_f32 v[42:43], v[42:43], v[188:189]
	v_pk_mul_f32 v[44:45], v[44:45], v[190:191]
	v_lshlrev_b32_e32 v102, 16, v122
	v_and_b32_e32 v122, 0xffff0000, v122
	v_lshlrev_b32_e32 v103, 16, v123
	v_and_b32_e32 v123, 0xffff0000, v123
	v_lshlrev_b32_e32 v104, 16, v124
	v_and_b32_e32 v124, 0xffff0000, v124
	v_lshlrev_b32_e32 v105, 16, v125
	v_and_b32_e32 v125, 0xffff0000, v125
	v_fma_f32 v50, v50, v166, v102
	v_fma_f32 v51, v51, v166, v122
	v_fma_f32 v52, v52, v166, v103
	v_fma_f32 v53, v53, v166, v123
	v_fma_f32 v42, v42, v166, v104
	v_fma_f32 v43, v43, v166, v124
	v_fma_f32 v44, v44, v166, v105
	v_fma_f32 v45, v45, v166, v125
	v_cvt_pk_bf16_f32 v50, v50, v51
	v_cvt_pk_bf16_f32 v51, v52, v53
	v_cvt_pk_bf16_f32 v52, v42, v43
	v_cvt_pk_bf16_f32 v53, v44, v45
	v_add_u32_e32 v156, 0x120000, v154
	global_store_dwordx4 v156, v[50:53], s[18:19] offset:0
	v_permlane16_swap_b32_e32 v38, v34
	v_permlane16_swap_b32_e32 v39, v35
	v_permlane16_swap_b32_e32 v40, v36
	v_permlane16_swap_b32_e32 v41, v37
	v_cvt_f32_i32_e32 v38, v38
	v_cvt_f32_i32_e32 v39, v39
	v_cvt_f32_i32_e32 v40, v40
	v_cvt_f32_i32_e32 v41, v41
	v_cvt_f32_i32_e32 v34, v34
	v_cvt_f32_i32_e32 v35, v35
	v_cvt_f32_i32_e32 v36, v36
	v_cvt_f32_i32_e32 v37, v37
	s_waitcnt vmcnt(15)
	v_pk_mul_f32 v[38:39], v[38:39], v[192:193]
	v_pk_mul_f32 v[40:41], v[40:41], v[194:195]
	v_pk_mul_f32 v[34:35], v[34:35], v[196:197]
	v_pk_mul_f32 v[36:37], v[36:37], v[198:199]
	v_lshlrev_b32_e32 v102, 16, v114
	v_and_b32_e32 v114, 0xffff0000, v114
	v_lshlrev_b32_e32 v103, 16, v115
	v_and_b32_e32 v115, 0xffff0000, v115
	v_lshlrev_b32_e32 v104, 16, v116
	v_and_b32_e32 v116, 0xffff0000, v116
	v_lshlrev_b32_e32 v105, 16, v117
	v_and_b32_e32 v117, 0xffff0000, v117
	v_fma_f32 v38, v38, v166, v102
	v_fma_f32 v39, v39, v166, v114
	v_fma_f32 v40, v40, v166, v103
	v_fma_f32 v41, v41, v166, v115
	v_fma_f32 v34, v34, v166, v104
	v_fma_f32 v35, v35, v166, v116
	v_fma_f32 v36, v36, v166, v105
	v_fma_f32 v37, v37, v166, v117
	v_cvt_pk_bf16_f32 v38, v38, v39
	v_cvt_pk_bf16_f32 v39, v40, v41
	v_cvt_pk_bf16_f32 v40, v34, v35
	v_cvt_pk_bf16_f32 v41, v36, v37
	v_add_u32_e32 v157, 0x120000, v154
	global_store_dwordx4 v157, v[38:41], s[18:19] offset:256
	v_permlane16_swap_b32_e32 v30, v26
	v_permlane16_swap_b32_e32 v31, v27
	v_permlane16_swap_b32_e32 v32, v28
	v_permlane16_swap_b32_e32 v33, v29
	v_cvt_f32_i32_e32 v30, v30
	v_cvt_f32_i32_e32 v31, v31
	v_cvt_f32_i32_e32 v32, v32
	v_cvt_f32_i32_e32 v33, v33
	v_cvt_f32_i32_e32 v26, v26
	v_cvt_f32_i32_e32 v27, v27
	v_cvt_f32_i32_e32 v28, v28
	v_cvt_f32_i32_e32 v29, v29
	s_waitcnt vmcnt(15)
	v_pk_mul_f32 v[30:31], v[30:31], v[184:185]
	v_pk_mul_f32 v[32:33], v[32:33], v[186:187]
	v_pk_mul_f32 v[26:27], v[26:27], v[188:189]
	v_pk_mul_f32 v[28:29], v[28:29], v[190:191]
	v_lshlrev_b32_e32 v102, 16, v106
	v_and_b32_e32 v106, 0xffff0000, v106
	v_lshlrev_b32_e32 v103, 16, v107
	v_and_b32_e32 v107, 0xffff0000, v107
	v_lshlrev_b32_e32 v104, 16, v108
	v_and_b32_e32 v108, 0xffff0000, v108
	v_lshlrev_b32_e32 v105, 16, v109
	v_and_b32_e32 v109, 0xffff0000, v109
	v_fma_f32 v30, v30, v167, v102
	v_fma_f32 v31, v31, v167, v106
	v_fma_f32 v32, v32, v167, v103
	v_fma_f32 v33, v33, v167, v107
	v_fma_f32 v26, v26, v167, v104
	v_fma_f32 v27, v27, v167, v108
	v_fma_f32 v28, v28, v167, v105
	v_fma_f32 v29, v29, v167, v109
	v_cvt_pk_bf16_f32 v30, v30, v31
	v_cvt_pk_bf16_f32 v31, v32, v33
	v_cvt_pk_bf16_f32 v32, v26, v27
	v_cvt_pk_bf16_f32 v33, v28, v29
	v_add_u32_e32 v156, 0x140000, v154
	global_store_dwordx4 v156, v[30:33], s[18:19] offset:0
	v_permlane16_swap_b32_e32 v22, v14
	v_permlane16_swap_b32_e32 v23, v15
	v_permlane16_swap_b32_e32 v24, v16
	v_permlane16_swap_b32_e32 v25, v17
	v_cvt_f32_i32_e32 v22, v22
	v_cvt_f32_i32_e32 v23, v23
	v_cvt_f32_i32_e32 v24, v24
	v_cvt_f32_i32_e32 v25, v25
	v_cvt_f32_i32_e32 v14, v14
	v_cvt_f32_i32_e32 v15, v15
	v_cvt_f32_i32_e32 v16, v16
	v_cvt_f32_i32_e32 v17, v17
	s_waitcnt vmcnt(15)
; __device__ __forceinline__ unsigned cvt_pk_bf16(float lo, float hi) { unsigned r; asm("v_cvt_pk_bf16_f32 %0, %1, %2" : "=v"(r) : "v"(lo), "v"(hi)); return r; }
; #define PG8_BAR __builtin_amdgcn_s_barrier()
; template <class Epi, class Geom, class Sched, bool ALIGN_EPI, bool I8 = false>
; __device__ __forceinline__ void gemm_phase(LAS unsigned char* lds, const Gemm g, const Sched& S, const Epi& E) {
;     ...
;         if (!has_next) break;
; #pragma unroll
;         for (int a = 0; a < 2; ++a)
; #pragma unroll
;             for (int b = 0; b < 2; ++b)
; #pragma unroll
;                 for (int m = 0; m < 4; ++m)
; #pragma unroll
;                     for (int n = 0; n < 2; ++n) acc[a][b][m][n] = (f32x4){0.f, 0.f, 0.f, 0.f};
;         cur = nxt; cA = nA; cB = nB; ++ui;
;         if constexpr (ALIGN_EPI) { if (wr == 1) PG8_BAR; }
;     __device__ __forceinline__ void operator()(const f32x4 (&acc)[2][2][4][2], const pg8::Unit& u, int wr, int wc, int fr, int fq) const {
;     ...
;             for (int mm = 0; mm < 2; ++mm) { const size_t off = (size_t)(row0 + ai * 128 + (m0 + mm) * 16) * DM + col0;
; #pragma unroll
;                 for (int bj = 0; bj < 2; ++bj)
; #pragma unroll
;                     for (int n = 0; n < 2; ++n) { const i32x4 q = __builtin_bit_cast(i32x4, acc[ai][bj][m0 + mm][n]);
;                         const f32x4 v = (f32x4){(float)q[0], (float)q[1], (float)q[2], (float)q[3]} * swv[bj][n] * sav[ai][m0 + mm] + r[mm][bj][n];
;                         u32x2 w; w.x = cvt_pk_bf16(v[0], v[1]); w.y = cvt_pk_bf16(v[2], v[3]); *(u32x2*)(X2 + off + bj * 128 + n * 16) = w; } } }
	v_pk_mul_f32 v[22:23], v[22:23], v[192:193]
	v_pk_mul_f32 v[24:25], v[24:25], v[194:195]
	v_pk_mul_f32 v[14:15], v[14:15], v[196:197]
	v_pk_mul_f32 v[16:17], v[16:17], v[198:199]
	v_lshlrev_b32_e32 v102, 16, v78
	v_and_b32_e32 v78, 0xffff0000, v78
	v_lshlrev_b32_e32 v103, 16, v79
	v_and_b32_e32 v79, 0xffff0000, v79
	v_lshlrev_b32_e32 v104, 16, v80
	v_and_b32_e32 v80, 0xffff0000, v80
	v_lshlrev_b32_e32 v105, 16, v81
	v_and_b32_e32 v81, 0xffff0000, v81
	v_fma_f32 v22, v22, v167, v102
	v_fma_f32 v23, v23, v167, v78
	v_fma_f32 v24, v24, v167, v103
	v_fma_f32 v25, v25, v167, v79
	v_fma_f32 v14, v14, v167, v104
	v_fma_f32 v15, v15, v167, v80
	v_fma_f32 v16, v16, v167, v105
	v_fma_f32 v17, v17, v167, v81
	v_cvt_pk_bf16_f32 v22, v22, v23
	v_cvt_pk_bf16_f32 v23, v24, v25
	v_cvt_pk_bf16_f32 v24, v14, v15
	v_cvt_pk_bf16_f32 v25, v16, v17
	v_add_u32_e32 v157, 0x140000, v154
	global_store_dwordx4 v157, v[22:25], s[18:19] offset:256
	v_permlane16_swap_b32_e32 v18, v10
	v_permlane16_swap_b32_e32 v19, v11
	v_permlane16_swap_b32_e32 v20, v12
	v_permlane16_swap_b32_e32 v21, v13
	v_cvt_f32_i32_e32 v18, v18
	v_cvt_f32_i32_e32 v19, v19
	v_cvt_f32_i32_e32 v20, v20
	v_cvt_f32_i32_e32 v21, v21
	v_cvt_f32_i32_e32 v10, v10
	v_cvt_f32_i32_e32 v11, v11
	v_cvt_f32_i32_e32 v12, v12
	v_cvt_f32_i32_e32 v13, v13
	s_waitcnt vmcnt(15)
	v_pk_mul_f32 v[18:19], v[18:19], v[184:185]
	v_pk_mul_f32 v[20:21], v[20:21], v[186:187]
	v_pk_mul_f32 v[10:11], v[10:11], v[188:189]
	v_pk_mul_f32 v[12:13], v[12:13], v[190:191]
	v_lshlrev_b32_e32 v102, 16, v74
	v_and_b32_e32 v74, 0xffff0000, v74
	v_lshlrev_b32_e32 v103, 16, v75
	v_and_b32_e32 v75, 0xffff0000, v75
	v_lshlrev_b32_e32 v104, 16, v76
	v_and_b32_e32 v76, 0xffff0000, v76
	v_lshlrev_b32_e32 v105, 16, v77
	v_and_b32_e32 v77, 0xffff0000, v77
	v_fma_f32 v18, v18, v168, v102
	v_fma_f32 v19, v19, v168, v74
	v_fma_f32 v20, v20, v168, v103
	v_fma_f32 v21, v21, v168, v75
	v_fma_f32 v10, v10, v168, v104
	v_fma_f32 v11, v11, v168, v76
	v_fma_f32 v12, v12, v168, v105
	v_fma_f32 v13, v13, v168, v77
	v_cvt_pk_bf16_f32 v18, v18, v19
	v_cvt_pk_bf16_f32 v19, v20, v21
	v_cvt_pk_bf16_f32 v20, v10, v11
	v_cvt_pk_bf16_f32 v21, v12, v13
	v_add_u32_e32 v156, 0x160000, v154
	global_store_dwordx4 v156, v[18:21], s[18:19] offset:0
	v_permlane16_swap_b32_e32 v6, v2
	v_permlane16_swap_b32_e32 v7, v3
	v_permlane16_swap_b32_e32 v8, v4
	v_permlane16_swap_b32_e32 v9, v5
	v_cvt_f32_i32_e32 v6, v6
	v_cvt_f32_i32_e32 v7, v7
	v_cvt_f32_i32_e32 v8, v8
	v_cvt_f32_i32_e32 v9, v9
	v_cvt_f32_i32_e32 v2, v2
	v_cvt_f32_i32_e32 v3, v3
	v_cvt_f32_i32_e32 v4, v4
	v_cvt_f32_i32_e32 v5, v5
	s_waitcnt vmcnt(15)
	v_pk_mul_f32 v[6:7], v[6:7], v[192:193]
	v_pk_mul_f32 v[8:9], v[8:9], v[194:195]
	v_pk_mul_f32 v[2:3], v[2:3], v[196:197]
	v_pk_mul_f32 v[4:5], v[4:5], v[198:199]
	v_lshlrev_b32_e32 v102, 16, v66
	v_and_b32_e32 v66, 0xffff0000, v66
	v_lshlrev_b32_e32 v103, 16, v67
	v_and_b32_e32 v67, 0xffff0000, v67
	v_lshlrev_b32_e32 v104, 16, v68
	v_and_b32_e32 v68, 0xffff0000, v68
	v_lshlrev_b32_e32 v105, 16, v69
	v_and_b32_e32 v69, 0xffff0000, v69
	v_fma_f32 v6, v6, v168, v102
	v_fma_f32 v7, v7, v168, v66
	v_fma_f32 v8, v8, v168, v103
	v_fma_f32 v9, v9, v168, v67
	v_fma_f32 v2, v2, v168, v104
	v_fma_f32 v3, v3, v168, v68
	v_fma_f32 v4, v4, v168, v105
	v_fma_f32 v5, v5, v168, v69
	v_cvt_pk_bf16_f32 v6, v6, v7
	v_cvt_pk_bf16_f32 v7, v8, v9
	v_cvt_pk_bf16_f32 v8, v2, v3
	v_cvt_pk_bf16_f32 v9, v4, v5
	v_add_u32_e32 v157, 0x160000, v154
	global_store_dwordx4 v157, v[6:9], s[18:19] offset:256
	s_and_b64 vcc, exec, s[4:5]
	s_mov_b64 s[4:5], -1
	s_cbranch_vccnz .LBB0_2864
	s_andn2_b64 vcc, exec, s[2:3]
	s_cbranch_vccnz .LBB0_2863
	s_barrier
	s_branch .LBB0_2863

; __device__ __forceinline__ unsigned cvt_pk_bf16(float lo, float hi) { unsigned r; asm("v_cvt_pk_bf16_f32 %0, %1, %2" : "=v"(r) : "v"(lo), "v"(hi)); return r; }
;     __device__ __forceinline__ void operator()(const f32x4 (&acc)[2][2][4][2], const pg8::Unit& u, int wr, int wc, int fr, int fq) const {
;         bf16_t* base = P + ((size_t)(u.tl * 8 + u.ks) << 16) + (size_t)(wr * 64 + fr) * 256 + wc * 32 + 4 * fq;
;         const int row0 = u.pm * 256 + wr * 64 + fr, col0 = u.pn * 256 + wc * 32 + 4 * fq;
;         f32x4 swv[2][2];
; #pragma unroll
;         for (int bj = 0; bj < 2; ++bj)
; #pragma unroll
;             for (int n = 0; n < 2; ++n) swv[bj][n] = *(const f32x4*)(sw + col0 + bj * 128 + n * 16);
; #pragma unroll
;         for (int ai = 0; ai < 2; ++ai)
; #pragma unroll
;             for (int m = 0; m < 4; ++m) { const float sav = sa[row0 + ai * 128 + m * 16];
; #pragma unroll
;                 for (int bj = 0; bj < 2; ++bj)
; #pragma unroll
;                     for (int n = 0; n < 2; ++n) { const i32x4 q = __builtin_bit_cast(i32x4, acc[ai][bj][m][n]);
;                         const f32x4 v = (f32x4){(float)q[0], (float)q[1], (float)q[2], (float)q[3]} * swv[bj][n] * sav;
;                         u32x2 o; o.x = cvt_pk_bf16(v[0], v[1]); o.y = cvt_pk_bf16(v[2], v[3]);
;                         *(u32x2*)(base + (size_t)(ai * 128 + m * 16) * 256 + bj * 128 + n * 16) = o; } }
;     }
.LBB0_2887:
	v_lshl_add_u32 v160, s24, 8, v146
	v_and_b32_e32 v161, 1, v235
	v_mul_u32_u24_e32 v161, 12, v161
	v_lshl_add_u32 v161, v235, 2, v161
	v_add_u32_e32 v161, s22, v161
	v_lshlrev_b32_e32 v164, 9, v146
	v_lshl_add_u32 v164, v161, 1, v164
	v_lshl_or_b32 v161, s25, 8, v161
	v_lshlrev_b32_e32 v163, 2, v161
	v_mbcnt_lo_u32_b32 v162, -1, 0
	v_mbcnt_hi_u32_b32 v162, -1, v162
	v_and_b32_e32 v194, 64, v146
	v_add_u32_e32 v162, v162, v194
	v_lshl_add_u32 v162, s24, 8, v162
	v_lshlrev_b32_e32 v162, 2, v162
	v_and_b32_e32 v194, 15, v146
	v_lshlrev_b32_e32 v194, 2, v194
	global_load_dword v192, v162, s[8:9]
	global_load_dword v193, v162, s[8:9] offset:512
	global_load_dwordx4 v[176:179], v163, s[10:11] offset:0
	global_load_dwordx4 v[180:183], v163, s[10:11] offset:16
	global_load_dwordx4 v[184:187], v163, s[10:11] offset:512
	global_load_dwordx4 v[188:191], v163, s[10:11] offset:528
	s_lshl_b32 s4, s21, 3
	s_add_i32 s4, s4, s20
	s_ashr_i32 s5, s4, 31
	s_lshl_b64 s[4:5], s[4:5], 17
	s_add_u32 s4, s86, s4
	s_addc_u32 s5, s87, s5
	s_add_u32 s4, s4, 0x2a50f000
	s_addc_u32 s5, s5, 0
	v_permlane16_swap_b32_e32 v142, v138
	v_permlane16_swap_b32_e32 v143, v139
	v_permlane16_swap_b32_e32 v144, v140
	v_permlane16_swap_b32_e32 v145, v141
	v_cvt_f32_i32_e32 v142, v142
	v_cvt_f32_i32_e32 v143, v143
	v_cvt_f32_i32_e32 v144, v144
	v_cvt_f32_i32_e32 v145, v145
	v_cvt_f32_i32_e32 v138, v138
	v_cvt_f32_i32_e32 v139, v139
	v_cvt_f32_i32_e32 v140, v140
	v_cvt_f32_i32_e32 v141, v141
	s_waitcnt vmcnt(0)
	ds_bpermute_b32 v168, v194, v192
	ds_bpermute_b32 v169, v194, v192 offset:64
	ds_bpermute_b32 v170, v194, v192 offset:128
	ds_bpermute_b32 v171, v194, v192 offset:192
	ds_bpermute_b32 v172, v194, v193
	ds_bpermute_b32 v173, v194, v193 offset:64
	ds_bpermute_b32 v174, v194, v193 offset:128
	ds_bpermute_b32 v175, v194, v193 offset:192
	s_waitcnt lgkmcnt(0)
	v_pk_mul_f32 v[142:143], v[142:143], v[176:177]
	v_pk_mul_f32 v[144:145], v[144:145], v[178:179]
	v_pk_mul_f32 v[138:139], v[138:139], v[180:181]
	v_pk_mul_f32 v[140:141], v[140:141], v[182:183]
	v_mul_f32_e32 v142, v142, v168
	v_mul_f32_e32 v143, v143, v168
	v_mul_f32_e32 v144, v144, v168
	v_mul_f32_e32 v145, v145, v168
	v_mul_f32_e32 v138, v138, v168
	v_mul_f32_e32 v139, v139, v168
	v_mul_f32_e32 v140, v140, v168
	v_mul_f32_e32 v141, v141, v168
	v_cvt_pk_bf16_f32 v142, v142, v143
	v_cvt_pk_bf16_f32 v143, v144, v145
	v_cvt_pk_bf16_f32 v144, v138, v139
	v_cvt_pk_bf16_f32 v145, v140, v141
	v_mov_b32_e32 v165, v164
	global_store_dwordx4 v165, v[142:145], s[4:5] offset:0
	v_permlane16_swap_b32_e32 v134, v130
	v_permlane16_swap_b32_e32 v135, v131
	v_permlane16_swap_b32_e32 v136, v132
	v_permlane16_swap_b32_e32 v137, v133
	v_cvt_f32_i32_e32 v134, v134
	v_cvt_f32_i32_e32 v135, v135
	v_cvt_f32_i32_e32 v136, v136
	v_cvt_f32_i32_e32 v137, v137
	v_cvt_f32_i32_e32 v130, v130
	v_cvt_f32_i32_e32 v131, v131
	v_cvt_f32_i32_e32 v132, v132
	v_cvt_f32_i32_e32 v133, v133
	v_pk_mul_f32 v[134:135], v[134:135], v[184:185]
	v_pk_mul_f32 v[136:137], v[136:137], v[186:187]
	v_pk_mul_f32 v[130:131], v[130:131], v[188:189]
	v_pk_mul_f32 v[132:133], v[132:133], v[190:191]
	v_mul_f32_e32 v134, v134, v168
	v_mul_f32_e32 v135, v135, v168
	v_mul_f32_e32 v136, v136, v168
	v_mul_f32_e32 v137, v137, v168
	v_mul_f32_e32 v130, v130, v168
	v_mul_f32_e32 v131, v131, v168
	v_mul_f32_e32 v132, v132, v168
	v_mul_f32_e32 v133, v133, v168
	v_cvt_pk_bf16_f32 v134, v134, v135
	v_cvt_pk_bf16_f32 v135, v136, v137
	v_cvt_pk_bf16_f32 v136, v130, v131
	v_cvt_pk_bf16_f32 v137, v132, v133
	v_mov_b32_e32 v166, v164
	global_store_dwordx4 v166, v[134:137], s[4:5] offset:256
	v_permlane16_swap_b32_e32 v126, v122
	v_permlane16_swap_b32_e32 v127, v123
	v_permlane16_swap_b32_e32 v128, v124
	v_permlane16_swap_b32_e32 v129, v125
	v_cvt_f32_i32_e32 v126, v126
	v_cvt_f32_i32_e32 v127, v127
	v_cvt_f32_i32_e32 v128, v128
	v_cvt_f32_i32_e32 v129, v129
	v_cvt_f32_i32_e32 v122, v122
	v_cvt_f32_i32_e32 v123, v123
	v_cvt_f32_i32_e32 v124, v124
	v_cvt_f32_i32_e32 v125, v125
	v_pk_mul_f32 v[126:127], v[126:127], v[176:177]
	v_pk_mul_f32 v[128:129], v[128:129], v[178:179]
	v_pk_mul_f32 v[122:123], v[122:123], v[180:181]
	v_pk_mul_f32 v[124:125], v[124:125], v[182:183]
	v_mul_f32_e32 v126, v126, v169
	v_mul_f32_e32 v127, v127, v169
	v_mul_f32_e32 v128, v128, v169
	v_mul_f32_e32 v129, v129, v169
	v_mul_f32_e32 v122, v122, v169
	v_mul_f32_e32 v123, v123, v169
	v_mul_f32_e32 v124, v124, v169
	v_mul_f32_e32 v125, v125, v169
	v_cvt_pk_bf16_f32 v126, v126, v127
	v_cvt_pk_bf16_f32 v127, v128, v129
	v_cvt_pk_bf16_f32 v128, v122, v123
	v_cvt_pk_bf16_f32 v129, v124, v125
	v_add_u32_e32 v165, 0x2000, v164
	global_store_dwordx4 v165, v[126:129], s[4:5] offset:0
	v_permlane16_swap_b32_e32 v102, v98
	v_permlane16_swap_b32_e32 v103, v99
	v_permlane16_swap_b32_e32 v104, v100
	v_permlane16_swap_b32_e32 v105, v101
	v_cvt_f32_i32_e32 v102, v102
	v_cvt_f32_i32_e32 v103, v103
	v_cvt_f32_i32_e32 v104, v104
	v_cvt_f32_i32_e32 v105, v105
	v_cvt_f32_i32_e32 v98, v98
	v_cvt_f32_i32_e32 v99, v99
	v_cvt_f32_i32_e32 v100, v100
	v_cvt_f32_i32_e32 v101, v101
	v_pk_mul_f32 v[102:103], v[102:103], v[184:185]
	v_pk_mul_f32 v[104:105], v[104:105], v[186:187]
	v_pk_mul_f32 v[98:99], v[98:99], v[188:189]
	v_pk_mul_f32 v[100:101], v[100:101], v[190:191]
	v_mul_f32_e32 v102, v102, v169
	v_mul_f32_e32 v103, v103, v169
	v_mul_f32_e32 v104, v104, v169
	v_mul_f32_e32 v105, v105, v169
	v_mul_f32_e32 v98, v98, v169
	v_mul_f32_e32 v99, v99, v169
	v_mul_f32_e32 v100, v100, v169
	v_mul_f32_e32 v101, v101, v169
	v_cvt_pk_bf16_f32 v102, v102, v103
	v_cvt_pk_bf16_f32 v103, v104, v105
	v_cvt_pk_bf16_f32 v104, v98, v99
; __device__ __forceinline__ unsigned cvt_pk_bf16(float lo, float hi) { unsigned r; asm("v_cvt_pk_bf16_f32 %0, %1, %2" : "=v"(r) : "v"(lo), "v"(hi)); return r; }
;     __device__ __forceinline__ void operator()(const f32x4 (&acc)[2][2][4][2], const pg8::Unit& u, int wr, int wc, int fr, int fq) const {
;     ...
;         for (int ai = 0; ai < 2; ++ai)
; #pragma unroll
;             for (int m = 0; m < 4; ++m) { const float sav = sa[row0 + ai * 128 + m * 16];
; #pragma unroll
;                 for (int bj = 0; bj < 2; ++bj)
; #pragma unroll
;                     for (int n = 0; n < 2; ++n) { const i32x4 q = __builtin_bit_cast(i32x4, acc[ai][bj][m][n]);
;                         const f32x4 v = (f32x4){(float)q[0], (float)q[1], (float)q[2], (float)q[3]} * swv[bj][n] * sav;
;                         u32x2 o; o.x = cvt_pk_bf16(v[0], v[1]); o.y = cvt_pk_bf16(v[2], v[3]);
;                         *(u32x2*)(base + (size_t)(ai * 128 + m * 16) * 256 + bj * 128 + n * 16) = o; } }
	v_cvt_pk_bf16_f32 v105, v100, v101
	v_add_u32_e32 v166, 0x2000, v164
	global_store_dwordx4 v166, v[102:105], s[4:5] offset:256
	v_permlane16_swap_b32_e32 v94, v90
	v_permlane16_swap_b32_e32 v95, v91
	v_permlane16_swap_b32_e32 v96, v92
	v_permlane16_swap_b32_e32 v97, v93
	v_cvt_f32_i32_e32 v94, v94
	v_cvt_f32_i32_e32 v95, v95
	v_cvt_f32_i32_e32 v96, v96
	v_cvt_f32_i32_e32 v97, v97
	v_cvt_f32_i32_e32 v90, v90
	v_cvt_f32_i32_e32 v91, v91
	v_cvt_f32_i32_e32 v92, v92
	v_cvt_f32_i32_e32 v93, v93
	v_pk_mul_f32 v[94:95], v[94:95], v[176:177]
	v_pk_mul_f32 v[96:97], v[96:97], v[178:179]
	v_pk_mul_f32 v[90:91], v[90:91], v[180:181]
	v_pk_mul_f32 v[92:93], v[92:93], v[182:183]
	v_mul_f32_e32 v94, v94, v170
	v_mul_f32_e32 v95, v95, v170
	v_mul_f32_e32 v96, v96, v170
	v_mul_f32_e32 v97, v97, v170
	v_mul_f32_e32 v90, v90, v170
	v_mul_f32_e32 v91, v91, v170
	v_mul_f32_e32 v92, v92, v170
	v_mul_f32_e32 v93, v93, v170
	v_cvt_pk_bf16_f32 v94, v94, v95
	v_cvt_pk_bf16_f32 v95, v96, v97
	v_cvt_pk_bf16_f32 v96, v90, v91
	v_cvt_pk_bf16_f32 v97, v92, v93
	v_add_u32_e32 v165, 0x4000, v164
	global_store_dwordx4 v165, v[94:97], s[4:5] offset:0
	v_permlane16_swap_b32_e32 v86, v82
	v_permlane16_swap_b32_e32 v87, v83
	v_permlane16_swap_b32_e32 v88, v84
	v_permlane16_swap_b32_e32 v89, v85
	v_cvt_f32_i32_e32 v86, v86
	v_cvt_f32_i32_e32 v87, v87
	v_cvt_f32_i32_e32 v88, v88
	v_cvt_f32_i32_e32 v89, v89
	v_cvt_f32_i32_e32 v82, v82
	v_cvt_f32_i32_e32 v83, v83
	v_cvt_f32_i32_e32 v84, v84
	v_cvt_f32_i32_e32 v85, v85
	v_pk_mul_f32 v[86:87], v[86:87], v[184:185]
	v_pk_mul_f32 v[88:89], v[88:89], v[186:187]
	v_pk_mul_f32 v[82:83], v[82:83], v[188:189]
	v_pk_mul_f32 v[84:85], v[84:85], v[190:191]
	v_mul_f32_e32 v86, v86, v170
	v_mul_f32_e32 v87, v87, v170
	v_mul_f32_e32 v88, v88, v170
	v_mul_f32_e32 v89, v89, v170
	v_mul_f32_e32 v82, v82, v170
	v_mul_f32_e32 v83, v83, v170
	v_mul_f32_e32 v84, v84, v170
	v_mul_f32_e32 v85, v85, v170
	v_cvt_pk_bf16_f32 v86, v86, v87
	v_cvt_pk_bf16_f32 v87, v88, v89
	v_cvt_pk_bf16_f32 v88, v82, v83
	v_cvt_pk_bf16_f32 v89, v84, v85
	v_add_u32_e32 v166, 0x4000, v164
	global_store_dwordx4 v166, v[86:89], s[4:5] offset:256
	v_permlane16_swap_b32_e32 v78, v74
	v_permlane16_swap_b32_e32 v79, v75
	v_permlane16_swap_b32_e32 v80, v76
	v_permlane16_swap_b32_e32 v81, v77
	v_cvt_f32_i32_e32 v78, v78
	v_cvt_f32_i32_e32 v79, v79
	v_cvt_f32_i32_e32 v80, v80
	v_cvt_f32_i32_e32 v81, v81
	v_cvt_f32_i32_e32 v74, v74
	v_cvt_f32_i32_e32 v75, v75
	v_cvt_f32_i32_e32 v76, v76
	v_cvt_f32_i32_e32 v77, v77
	v_pk_mul_f32 v[78:79], v[78:79], v[176:177]
	v_pk_mul_f32 v[80:81], v[80:81], v[178:179]
	v_pk_mul_f32 v[74:75], v[74:75], v[180:181]
	v_pk_mul_f32 v[76:77], v[76:77], v[182:183]
	v_mul_f32_e32 v78, v78, v171
	v_mul_f32_e32 v79, v79, v171
	v_mul_f32_e32 v80, v80, v171
	v_mul_f32_e32 v81, v81, v171
	v_mul_f32_e32 v74, v74, v171
	v_mul_f32_e32 v75, v75, v171
	v_mul_f32_e32 v76, v76, v171
	v_mul_f32_e32 v77, v77, v171
	v_cvt_pk_bf16_f32 v78, v78, v79
	v_cvt_pk_bf16_f32 v79, v80, v81
	v_cvt_pk_bf16_f32 v80, v74, v75
	v_cvt_pk_bf16_f32 v81, v76, v77
	v_add_u32_e32 v165, 0x6000, v164
	global_store_dwordx4 v165, v[78:81], s[4:5] offset:0
	v_permlane16_swap_b32_e32 v70, v66
	v_permlane16_swap_b32_e32 v71, v67
	v_permlane16_swap_b32_e32 v72, v68
	v_permlane16_swap_b32_e32 v73, v69
	v_cvt_f32_i32_e32 v70, v70
	v_cvt_f32_i32_e32 v71, v71
	v_cvt_f32_i32_e32 v72, v72
	v_cvt_f32_i32_e32 v73, v73
	v_cvt_f32_i32_e32 v66, v66
	v_cvt_f32_i32_e32 v67, v67
	v_cvt_f32_i32_e32 v68, v68
	v_cvt_f32_i32_e32 v69, v69
	v_pk_mul_f32 v[70:71], v[70:71], v[184:185]
	v_pk_mul_f32 v[72:73], v[72:73], v[186:187]
	v_pk_mul_f32 v[66:67], v[66:67], v[188:189]
	v_pk_mul_f32 v[68:69], v[68:69], v[190:191]
	v_mul_f32_e32 v70, v70, v171
	v_mul_f32_e32 v71, v71, v171
	v_mul_f32_e32 v72, v72, v171
	v_mul_f32_e32 v73, v73, v171
	v_mul_f32_e32 v66, v66, v171
	v_mul_f32_e32 v67, v67, v171
	v_mul_f32_e32 v68, v68, v171
	v_mul_f32_e32 v69, v69, v171
	v_cvt_pk_bf16_f32 v70, v70, v71
	v_cvt_pk_bf16_f32 v71, v72, v73
	v_cvt_pk_bf16_f32 v72, v66, v67
	v_cvt_pk_bf16_f32 v73, v68, v69
	v_add_u32_e32 v166, 0x6000, v164
	global_store_dwordx4 v166, v[70:73], s[4:5] offset:256
	v_permlane16_swap_b32_e32 v62, v58
	v_permlane16_swap_b32_e32 v63, v59
	v_permlane16_swap_b32_e32 v64, v60
	v_permlane16_swap_b32_e32 v65, v61
	v_cvt_f32_i32_e32 v62, v62
	v_cvt_f32_i32_e32 v63, v63
	v_cvt_f32_i32_e32 v64, v64
	v_cvt_f32_i32_e32 v65, v65
	v_cvt_f32_i32_e32 v58, v58
	v_cvt_f32_i32_e32 v59, v59
	v_cvt_f32_i32_e32 v60, v60
	v_cvt_f32_i32_e32 v61, v61
	v_pk_mul_f32 v[62:63], v[62:63], v[176:177]
	v_pk_mul_f32 v[64:65], v[64:65], v[178:179]
	v_pk_mul_f32 v[58:59], v[58:59], v[180:181]
	v_pk_mul_f32 v[60:61], v[60:61], v[182:183]
	v_mul_f32_e32 v62, v62, v172
	v_mul_f32_e32 v63, v63, v172
	v_mul_f32_e32 v64, v64, v172
	v_mul_f32_e32 v65, v65, v172
	v_mul_f32_e32 v58, v58, v172
	v_mul_f32_e32 v59, v59, v172
	v_mul_f32_e32 v60, v60, v172
	v_mul_f32_e32 v61, v61, v172
	v_cvt_pk_bf16_f32 v62, v62, v63
	v_cvt_pk_bf16_f32 v63, v64, v65
	v_cvt_pk_bf16_f32 v64, v58, v59
	v_cvt_pk_bf16_f32 v65, v60, v61
	v_add_u32_e32 v165, 0x10000, v164
	global_store_dwordx4 v165, v[62:65], s[4:5] offset:0
	v_permlane16_swap_b32_e32 v54, v50
	v_permlane16_swap_b32_e32 v55, v51
	v_permlane16_swap_b32_e32 v56, v52
	v_permlane16_swap_b32_e32 v57, v53
	v_cvt_f32_i32_e32 v54, v54
	v_cvt_f32_i32_e32 v55, v55
	v_cvt_f32_i32_e32 v56, v56
	v_cvt_f32_i32_e32 v57, v57
	v_cvt_f32_i32_e32 v50, v50
	v_cvt_f32_i32_e32 v51, v51
	v_cvt_f32_i32_e32 v52, v52
	v_cvt_f32_i32_e32 v53, v53
	v_pk_mul_f32 v[54:55], v[54:55], v[184:185]
	v_pk_mul_f32 v[56:57], v[56:57], v[186:187]
; __device__ __forceinline__ unsigned cvt_pk_bf16(float lo, float hi) { unsigned r; asm("v_cvt_pk_bf16_f32 %0, %1, %2" : "=v"(r) : "v"(lo), "v"(hi)); return r; }
; #define PG8_WAIT_V(n) asm volatile("s_waitcnt vmcnt(" #n ")" ::: "memory")
; #define PG8_BAR __builtin_amdgcn_s_barrier()
; template <class Epi, class Geom, class Sched, bool ALIGN_EPI, bool I8 = false>
; __device__ __forceinline__ void gemm_phase(LAS unsigned char* lds, const Gemm g, const Sched& S, const Epi& E) {
;     ...
;     PG8_WAIT_V(0);
;     if constexpr (!ALIGN_EPI) { if (wr == 0) PG8_BAR; }
;     PG8_BAR;
;     __device__ __forceinline__ void operator()(const f32x4 (&acc)[2][2][4][2], const pg8::Unit& u, int wr, int wc, int fr, int fq) const {
;     ...
;                 for (int bj = 0; bj < 2; ++bj)
; #pragma unroll
;                     for (int n = 0; n < 2; ++n) { const i32x4 q = __builtin_bit_cast(i32x4, acc[ai][bj][m][n]);
;                         const f32x4 v = (f32x4){(float)q[0], (float)q[1], (float)q[2], (float)q[3]} * swv[bj][n] * sav;
;                         u32x2 o; o.x = cvt_pk_bf16(v[0], v[1]); o.y = cvt_pk_bf16(v[2], v[3]);
;                         *(u32x2*)(base + (size_t)(ai * 128 + m * 16) * 256 + bj * 128 + n * 16) = o; } }
	v_pk_mul_f32 v[50:51], v[50:51], v[188:189]
	v_pk_mul_f32 v[52:53], v[52:53], v[190:191]
	v_mul_f32_e32 v54, v54, v172
	v_mul_f32_e32 v55, v55, v172
	v_mul_f32_e32 v56, v56, v172
	v_mul_f32_e32 v57, v57, v172
	v_mul_f32_e32 v50, v50, v172
	v_mul_f32_e32 v51, v51, v172
	v_mul_f32_e32 v52, v52, v172
	v_mul_f32_e32 v53, v53, v172
	v_cvt_pk_bf16_f32 v54, v54, v55
	v_cvt_pk_bf16_f32 v55, v56, v57
	v_cvt_pk_bf16_f32 v56, v50, v51
	v_cvt_pk_bf16_f32 v57, v52, v53
	v_add_u32_e32 v166, 0x10000, v164
	global_store_dwordx4 v166, v[54:57], s[4:5] offset:256
	v_permlane16_swap_b32_e32 v46, v42
	v_permlane16_swap_b32_e32 v47, v43
	v_permlane16_swap_b32_e32 v48, v44
	v_permlane16_swap_b32_e32 v49, v45
	v_cvt_f32_i32_e32 v46, v46
	v_cvt_f32_i32_e32 v47, v47
	v_cvt_f32_i32_e32 v48, v48
	v_cvt_f32_i32_e32 v49, v49
	v_cvt_f32_i32_e32 v42, v42
	v_cvt_f32_i32_e32 v43, v43
	v_cvt_f32_i32_e32 v44, v44
	v_cvt_f32_i32_e32 v45, v45
	v_pk_mul_f32 v[46:47], v[46:47], v[176:177]
	v_pk_mul_f32 v[48:49], v[48:49], v[178:179]
	v_pk_mul_f32 v[42:43], v[42:43], v[180:181]
	v_pk_mul_f32 v[44:45], v[44:45], v[182:183]
	v_mul_f32_e32 v46, v46, v173
	v_mul_f32_e32 v47, v47, v173
	v_mul_f32_e32 v48, v48, v173
	v_mul_f32_e32 v49, v49, v173
	v_mul_f32_e32 v42, v42, v173
	v_mul_f32_e32 v43, v43, v173
	v_mul_f32_e32 v44, v44, v173
	v_mul_f32_e32 v45, v45, v173
	v_cvt_pk_bf16_f32 v46, v46, v47
	v_cvt_pk_bf16_f32 v47, v48, v49
	v_cvt_pk_bf16_f32 v48, v42, v43
	v_cvt_pk_bf16_f32 v49, v44, v45
	v_add_u32_e32 v165, 0x12000, v164
	global_store_dwordx4 v165, v[46:49], s[4:5] offset:0
	v_permlane16_swap_b32_e32 v38, v34
	v_permlane16_swap_b32_e32 v39, v35
	v_permlane16_swap_b32_e32 v40, v36
	v_permlane16_swap_b32_e32 v41, v37
	v_cvt_f32_i32_e32 v38, v38
	v_cvt_f32_i32_e32 v39, v39
	v_cvt_f32_i32_e32 v40, v40
	v_cvt_f32_i32_e32 v41, v41
	v_cvt_f32_i32_e32 v34, v34
	v_cvt_f32_i32_e32 v35, v35
	v_cvt_f32_i32_e32 v36, v36
	v_cvt_f32_i32_e32 v37, v37
	v_pk_mul_f32 v[38:39], v[38:39], v[184:185]
	v_pk_mul_f32 v[40:41], v[40:41], v[186:187]
	v_pk_mul_f32 v[34:35], v[34:35], v[188:189]
	v_pk_mul_f32 v[36:37], v[36:37], v[190:191]
	v_mul_f32_e32 v38, v38, v173
	v_mul_f32_e32 v39, v39, v173
	v_mul_f32_e32 v40, v40, v173
	v_mul_f32_e32 v41, v41, v173
	v_mul_f32_e32 v34, v34, v173
	v_mul_f32_e32 v35, v35, v173
	v_mul_f32_e32 v36, v36, v173
	v_mul_f32_e32 v37, v37, v173
	v_cvt_pk_bf16_f32 v38, v38, v39
	v_cvt_pk_bf16_f32 v39, v40, v41
	v_cvt_pk_bf16_f32 v40, v34, v35
	v_cvt_pk_bf16_f32 v41, v36, v37
	v_add_u32_e32 v166, 0x12000, v164
	global_store_dwordx4 v166, v[38:41], s[4:5] offset:256
	v_permlane16_swap_b32_e32 v30, v26
	v_permlane16_swap_b32_e32 v31, v27
	v_permlane16_swap_b32_e32 v32, v28
	v_permlane16_swap_b32_e32 v33, v29
	v_cvt_f32_i32_e32 v30, v30
	v_cvt_f32_i32_e32 v31, v31
	v_cvt_f32_i32_e32 v32, v32
	v_cvt_f32_i32_e32 v33, v33
	v_cvt_f32_i32_e32 v26, v26
	v_cvt_f32_i32_e32 v27, v27
	v_cvt_f32_i32_e32 v28, v28
	v_cvt_f32_i32_e32 v29, v29
	v_pk_mul_f32 v[30:31], v[30:31], v[176:177]
	v_pk_mul_f32 v[32:33], v[32:33], v[178:179]
	v_pk_mul_f32 v[26:27], v[26:27], v[180:181]
	v_pk_mul_f32 v[28:29], v[28:29], v[182:183]
	v_mul_f32_e32 v30, v30, v174
	v_mul_f32_e32 v31, v31, v174
	v_mul_f32_e32 v32, v32, v174
	v_mul_f32_e32 v33, v33, v174
	v_mul_f32_e32 v26, v26, v174
	v_mul_f32_e32 v27, v27, v174
	v_mul_f32_e32 v28, v28, v174
	v_mul_f32_e32 v29, v29, v174
	v_cvt_pk_bf16_f32 v30, v30, v31
	v_cvt_pk_bf16_f32 v31, v32, v33
	v_cvt_pk_bf16_f32 v32, v26, v27
	v_cvt_pk_bf16_f32 v33, v28, v29
	v_add_u32_e32 v165, 0x14000, v164
	global_store_dwordx4 v165, v[30:33], s[4:5] offset:0
	v_permlane16_swap_b32_e32 v22, v18
	v_permlane16_swap_b32_e32 v23, v19
	v_permlane16_swap_b32_e32 v24, v20
	v_permlane16_swap_b32_e32 v25, v21
	v_cvt_f32_i32_e32 v22, v22
	v_cvt_f32_i32_e32 v23, v23
	v_cvt_f32_i32_e32 v24, v24
	v_cvt_f32_i32_e32 v25, v25
	v_cvt_f32_i32_e32 v18, v18
	v_cvt_f32_i32_e32 v19, v19
	v_cvt_f32_i32_e32 v20, v20
	v_cvt_f32_i32_e32 v21, v21
	v_pk_mul_f32 v[22:23], v[22:23], v[184:185]
	v_pk_mul_f32 v[24:25], v[24:25], v[186:187]
	v_pk_mul_f32 v[18:19], v[18:19], v[188:189]
	v_pk_mul_f32 v[20:21], v[20:21], v[190:191]
	v_mul_f32_e32 v22, v22, v174
	v_mul_f32_e32 v23, v23, v174
	v_mul_f32_e32 v24, v24, v174
	v_mul_f32_e32 v25, v25, v174
	v_mul_f32_e32 v18, v18, v174
	v_mul_f32_e32 v19, v19, v174
	v_mul_f32_e32 v20, v20, v174
	v_mul_f32_e32 v21, v21, v174
	v_cvt_pk_bf16_f32 v22, v22, v23
	v_cvt_pk_bf16_f32 v23, v24, v25
	v_cvt_pk_bf16_f32 v24, v18, v19
	v_cvt_pk_bf16_f32 v25, v20, v21
	v_add_u32_e32 v166, 0x14000, v164
	global_store_dwordx4 v166, v[22:25], s[4:5] offset:256
	v_permlane16_swap_b32_e32 v14, v10
	v_permlane16_swap_b32_e32 v15, v11
	v_permlane16_swap_b32_e32 v16, v12
	v_permlane16_swap_b32_e32 v17, v13
	v_cvt_f32_i32_e32 v14, v14
	v_cvt_f32_i32_e32 v15, v15
	v_cvt_f32_i32_e32 v16, v16
	v_cvt_f32_i32_e32 v17, v17
	v_cvt_f32_i32_e32 v10, v10
	v_cvt_f32_i32_e32 v11, v11
	v_cvt_f32_i32_e32 v12, v12
	v_cvt_f32_i32_e32 v13, v13
	v_pk_mul_f32 v[14:15], v[14:15], v[176:177]
	v_pk_mul_f32 v[16:17], v[16:17], v[178:179]
	v_pk_mul_f32 v[10:11], v[10:11], v[180:181]
	v_pk_mul_f32 v[12:13], v[12:13], v[182:183]
	v_mul_f32_e32 v14, v14, v175
	v_mul_f32_e32 v15, v15, v175
	v_mul_f32_e32 v16, v16, v175
	v_mul_f32_e32 v17, v17, v175
	v_mul_f32_e32 v10, v10, v175
	v_mul_f32_e32 v11, v11, v175
	v_mul_f32_e32 v12, v12, v175
	v_mul_f32_e32 v13, v13, v175
	v_cvt_pk_bf16_f32 v14, v14, v15
	v_cvt_pk_bf16_f32 v15, v16, v17
	v_cvt_pk_bf16_f32 v16, v10, v11
	v_cvt_pk_bf16_f32 v17, v12, v13
	v_add_u32_e32 v165, 0x16000, v164
	global_store_dwordx4 v165, v[14:17], s[4:5] offset:0
	v_permlane16_swap_b32_e32 v6, v2
	v_permlane16_swap_b32_e32 v7, v3
	v_permlane16_swap_b32_e32 v8, v4
	v_permlane16_swap_b32_e32 v9, v5
	v_cvt_f32_i32_e32 v6, v6
	v_cvt_f32_i32_e32 v7, v7
	v_cvt_f32_i32_e32 v8, v8
	v_cvt_f32_i32_e32 v9, v9
	v_cvt_f32_i32_e32 v2, v2
	v_cvt_f32_i32_e32 v3, v3
	v_cvt_f32_i32_e32 v4, v4
	v_cvt_f32_i32_e32 v5, v5
	v_pk_mul_f32 v[6:7], v[6:7], v[184:185]
	v_pk_mul_f32 v[8:9], v[8:9], v[186:187]
	v_pk_mul_f32 v[2:3], v[2:3], v[188:189]
	v_pk_mul_f32 v[4:5], v[4:5], v[190:191]
	v_mul_f32_e32 v6, v6, v175
	v_mul_f32_e32 v7, v7, v175
	v_mul_f32_e32 v8, v8, v175
	v_mul_f32_e32 v9, v9, v175
	v_mul_f32_e32 v2, v2, v175
	v_mul_f32_e32 v3, v3, v175
	v_mul_f32_e32 v4, v4, v175
	v_mul_f32_e32 v5, v5, v175
	v_cvt_pk_bf16_f32 v6, v6, v7
	v_cvt_pk_bf16_f32 v7, v8, v9
	v_cvt_pk_bf16_f32 v8, v2, v3
	v_cvt_pk_bf16_f32 v9, v4, v5
	v_add_u32_e32 v166, 0x16000, v164
	global_store_dwordx4 v166, v[6:9], s[4:5] offset:256
	s_waitcnt vmcnt(0)
	s_barrier
